# saddr-form LDS-DMA loads (scalar base + 32-bit VGPR offset) in all six GEMM K-loops: 46 64-bit VALU address adds removed from the load sections
# speedup vs baseline: 1.0023x; 1.0023x over previous
.LBB0_239:
	s_add_i32 s41, s16, 2
	s_add_u32 s17, s14, 0xfffc0080
	s_addc_u32 s18, s15, -1
	s_add_i32 s42, 0, 0x10000
	v_add_u32_e32 v149, s42, v1
	ds_read_b128 v[156:159], v149
	ds_read_b128 v[160:163], v149 offset:1024
	ds_read_b128 v[164:167], v149 offset:2048
	ds_read_b128 v[168:171], v149 offset:3072
	s_cmp_eq_u32 s31, s16
	s_cselect_b32 s16, s38, s39
	s_cselect_b32 s19, s7, s18
	s_cselect_b32 s18, s9, s17
	s_cselect_b32 s17, s37, s40
	s_add_i32 m0, s23, 0xc000
	ds_read_b128 v[172:175], v151
	ds_read_b128 v[176:179], v151 offset:1024
	ds_read_b128 v[180:183], v151 offset:2048
	ds_read_b128 v[184:187], v151 offset:3072
	ds_read_b128 v[188:191], v151 offset:4096
	ds_read_b128 v[192:195], v151 offset:5120
	ds_read_b128 v[196:199], v151 offset:6144
	ds_read_b128 v[200:203], v151 offset:7168
	global_load_lds_dwordx4 v140, s[14:15]
	s_add_i32 m0, s23, 0xe000
	s_nop 0
	global_load_lds_dwordx4 v142, s[14:15]
	s_waitcnt lgkmcnt(8)
	s_barrier
	s_waitcnt lgkmcnt(0)
	s_setprio 1
	s_waitcnt lgkmcnt(0)
	v_mfma_f32_16x16x32_bf16 v[122:125], v[156:159], v[172:175], v[122:125]
	v_mfma_f32_16x16x32_bf16 v[126:129], v[164:167], v[172:175], v[126:129]
	v_mfma_f32_16x16x32_bf16 v[106:109], v[156:159], v[180:183], v[106:109]
	v_mfma_f32_16x16x32_bf16 v[110:113], v[164:167], v[180:183], v[110:113]
	v_mfma_f32_16x16x32_bf16 v[90:93], v[156:159], v[188:191], v[90:93]
	v_mfma_f32_16x16x32_bf16 v[94:97], v[164:167], v[188:191], v[94:97]
	v_mfma_f32_16x16x32_bf16 v[74:77], v[156:159], v[196:199], v[74:77]
	v_mfma_f32_16x16x32_bf16 v[78:81], v[164:167], v[196:199], v[78:81]
	v_mfma_f32_16x16x32_bf16 v[122:125], v[160:163], v[176:179], v[122:125]
	v_mfma_f32_16x16x32_bf16 v[126:129], v[168:171], v[176:179], v[126:129]
	v_mfma_f32_16x16x32_bf16 v[106:109], v[160:163], v[184:187], v[106:109]
	v_mfma_f32_16x16x32_bf16 v[110:113], v[168:171], v[184:187], v[110:113]
	v_mfma_f32_16x16x32_bf16 v[90:93], v[160:163], v[192:195], v[90:93]
	v_mfma_f32_16x16x32_bf16 v[94:97], v[168:171], v[192:195], v[94:97]
	v_mfma_f32_16x16x32_bf16 v[74:77], v[160:163], v[200:203], v[74:77]
	v_mfma_f32_16x16x32_bf16 v[78:81], v[168:171], v[200:203], v[78:81]
	s_setprio 0
	s_barrier
	s_add_i32 s44, 0, 0x14000
	s_add_i32 s42, s42, s22
	v_add_u32_e32 v149, s44, v1
	v_lshl_add_u64 v[230:231], s[16:17], 0, v[134:135]
	s_mov_b32 m0, s42
	ds_read_b128 v[204:207], v149
	ds_read_b128 v[208:211], v149 offset:1024
	ds_read_b128 v[212:215], v149 offset:2048
	ds_read_b128 v[226:229], v149 offset:3072
	global_load_lds_dwordx4 v[230:231], off
	v_lshl_add_u64 v[232:233], s[16:17], 0, v[130:131]
	s_add_i32 m0, s42, 0x2000
	s_nop 0
	global_load_lds_dwordx4 v[232:233], off
	s_barrier
	s_waitcnt lgkmcnt(0)
	s_setprio 1
	s_waitcnt lgkmcnt(0)
	v_mfma_f32_16x16x32_bf16 v[114:117], v[204:207], v[172:175], v[114:117]
	v_mfma_f32_16x16x32_bf16 v[118:121], v[212:215], v[172:175], v[118:121]
	v_mfma_f32_16x16x32_bf16 v[98:101], v[204:207], v[180:183], v[98:101]
	v_mfma_f32_16x16x32_bf16 v[102:105], v[212:215], v[180:183], v[102:105]
	v_mfma_f32_16x16x32_bf16 v[82:85], v[204:207], v[188:191], v[82:85]
	v_mfma_f32_16x16x32_bf16 v[86:89], v[212:215], v[188:191], v[86:89]
	v_mfma_f32_16x16x32_bf16 v[66:69], v[204:207], v[196:199], v[66:69]
	v_mfma_f32_16x16x32_bf16 v[70:73], v[212:215], v[196:199], v[70:73]
	v_mfma_f32_16x16x32_bf16 v[114:117], v[208:211], v[176:179], v[114:117]
	v_mfma_f32_16x16x32_bf16 v[118:121], v[226:229], v[176:179], v[118:121]
	v_mfma_f32_16x16x32_bf16 v[98:101], v[208:211], v[184:187], v[98:101]
	v_mfma_f32_16x16x32_bf16 v[102:105], v[226:229], v[184:187], v[102:105]
	v_mfma_f32_16x16x32_bf16 v[82:85], v[208:211], v[192:195], v[82:85]
	v_mfma_f32_16x16x32_bf16 v[86:89], v[226:229], v[192:195], v[86:89]
	v_mfma_f32_16x16x32_bf16 v[66:69], v[208:211], v[200:203], v[66:69]
	v_mfma_f32_16x16x32_bf16 v[70:73], v[226:229], v[200:203], v[70:73]
	s_setprio 0
	s_mov_b32 m0, s23
	v_lshl_add_u64 v[234:235], s[18:19], 0, v[136:137]
	s_barrier
	ds_read_b128 v[172:175], v151 offset:16384
	ds_read_b128 v[176:179], v151 offset:17408
	ds_read_b128 v[180:183], v151 offset:18432
	ds_read_b128 v[184:187], v151 offset:19456
	ds_read_b128 v[188:191], v151 offset:20480
	ds_read_b128 v[192:195], v151 offset:21504
	ds_read_b128 v[196:199], v151 offset:22528
	ds_read_b128 v[200:203], v151 offset:23552
	global_load_lds_dwordx4 v[234:235], off
	v_lshl_add_u64 v[236:237], s[18:19], 0, v[132:133]
	s_mov_b32 m0, s24
	s_nop 0
	global_load_lds_dwordx4 v[236:237], off
	s_barrier
	s_waitcnt lgkmcnt(0)
	s_setprio 1
	s_waitcnt lgkmcnt(0)
	v_mfma_f32_16x16x32_bf16 v[58:61], v[156:159], v[172:175], v[58:61]
	v_mfma_f32_16x16x32_bf16 v[62:65], v[164:167], v[172:175], v[62:65]
	v_mfma_f32_16x16x32_bf16 v[42:45], v[156:159], v[180:183], v[42:45]
	v_mfma_f32_16x16x32_bf16 v[46:49], v[164:167], v[180:183], v[46:49]
	v_mfma_f32_16x16x32_bf16 v[26:29], v[156:159], v[188:191], v[26:29]
	v_mfma_f32_16x16x32_bf16 v[30:33], v[164:167], v[188:191], v[30:33]
	v_mfma_f32_16x16x32_bf16 v[10:13], v[156:159], v[196:199], v[10:13]
	v_mfma_f32_16x16x32_bf16 v[14:17], v[164:167], v[196:199], v[14:17]
	v_mfma_f32_16x16x32_bf16 v[58:61], v[160:163], v[176:179], v[58:61]
	v_mfma_f32_16x16x32_bf16 v[62:65], v[168:171], v[176:179], v[62:65]
	v_mfma_f32_16x16x32_bf16 v[42:45], v[160:163], v[184:187], v[42:45]
	v_mfma_f32_16x16x32_bf16 v[46:49], v[168:171], v[184:187], v[46:49]
	v_mfma_f32_16x16x32_bf16 v[26:29], v[160:163], v[192:195], v[26:29]
	v_mfma_f32_16x16x32_bf16 v[30:33], v[168:171], v[192:195], v[30:33]
	v_mfma_f32_16x16x32_bf16 v[10:13], v[160:163], v[200:203], v[10:13]
	v_mfma_f32_16x16x32_bf16 v[14:17], v[168:171], v[200:203], v[14:17]
	s_setprio 0
	s_barrier
	s_add_u32 s42, s16, 0x40000
	s_addc_u32 s43, s17, 0
	s_add_i32 s44, s44, s22
	s_mov_b32 m0, s44
	s_nop 0
	global_load_lds_dwordx4 v134, s[42:43]
	s_add_i32 m0, s44, 0x2000
	s_nop 0
	global_load_lds_dwordx4 v130, s[42:43]
	s_cmp_eq_u32 s100, 0
	s_cbranch_scc1 .Lip_w4n
	s_waitcnt vmcnt(24)
	s_branch .Lip_w4d

.Lip_w4d:
	s_barrier
	s_setprio 1
	v_mfma_f32_16x16x32_bf16 v[50:53], v[204:207], v[172:175], v[50:53]
	v_mfma_f32_16x16x32_bf16 v[54:57], v[212:215], v[172:175], v[54:57]
	v_mfma_f32_16x16x32_bf16 v[34:37], v[204:207], v[180:183], v[34:37]
	v_mfma_f32_16x16x32_bf16 v[38:41], v[212:215], v[180:183], v[38:41]
	v_mfma_f32_16x16x32_bf16 v[18:21], v[204:207], v[188:191], v[18:21]
	v_mfma_f32_16x16x32_bf16 v[22:25], v[212:215], v[188:191], v[22:25]
	v_mfma_f32_16x16x32_bf16 v[6:9], v[204:207], v[196:199], v[6:9]
	v_mfma_f32_16x16x32_bf16 v[2:5], v[212:215], v[196:199], v[2:5]
	v_mfma_f32_16x16x32_bf16 v[50:53], v[208:211], v[176:179], v[50:53]
	v_mfma_f32_16x16x32_bf16 v[54:57], v[226:229], v[176:179], v[54:57]
	v_mfma_f32_16x16x32_bf16 v[34:37], v[208:211], v[184:187], v[34:37]
	v_mfma_f32_16x16x32_bf16 v[38:41], v[226:229], v[184:187], v[38:41]
	v_mfma_f32_16x16x32_bf16 v[18:21], v[208:211], v[192:195], v[18:21]
	v_mfma_f32_16x16x32_bf16 v[22:25], v[226:229], v[192:195], v[22:25]
	v_mfma_f32_16x16x32_bf16 v[6:9], v[208:211], v[200:203], v[6:9]
	v_mfma_f32_16x16x32_bf16 v[2:5], v[226:229], v[200:203], v[2:5]
	s_setprio 0
	s_add_i32 s42, 0, 0x18000
	v_add_u32_e32 v149, s42, v1
	s_barrier
	ds_read_b128 v[156:159], v149
	ds_read_b128 v[160:163], v149 offset:1024
	ds_read_b128 v[164:167], v149 offset:2048
	ds_read_b128 v[168:171], v149 offset:3072
	s_add_u32 s18, s18, 0x40000
	s_addc_u32 s19, s19, 0
	s_mov_b32 m0, s25
	ds_read_b128 v[172:175], v151 offset:32768
	ds_read_b128 v[176:179], v151 offset:33792
	ds_read_b128 v[180:183], v151 offset:34816
	ds_read_b128 v[184:187], v151 offset:35840
	ds_read_b128 v[188:191], v151 offset:36864
	ds_read_b128 v[192:195], v151 offset:37888
	ds_read_b128 v[196:199], v151 offset:38912
	ds_read_b128 v[200:203], v151 offset:39936
	global_load_lds_dwordx4 v136, s[18:19]
	s_mov_b32 m0, s26
	s_nop 0
	global_load_lds_dwordx4 v132, s[18:19]
	s_waitcnt lgkmcnt(8)
	s_barrier
	s_waitcnt lgkmcnt(0)
	s_setprio 1
	s_waitcnt lgkmcnt(0)
	v_mfma_f32_16x16x32_bf16 v[122:125], v[156:159], v[172:175], v[122:125]
	v_mfma_f32_16x16x32_bf16 v[126:129], v[164:167], v[172:175], v[126:129]
	v_mfma_f32_16x16x32_bf16 v[106:109], v[156:159], v[180:183], v[106:109]
	v_mfma_f32_16x16x32_bf16 v[110:113], v[164:167], v[180:183], v[110:113]
	v_mfma_f32_16x16x32_bf16 v[90:93], v[156:159], v[188:191], v[90:93]
	v_mfma_f32_16x16x32_bf16 v[94:97], v[164:167], v[188:191], v[94:97]
	v_mfma_f32_16x16x32_bf16 v[74:77], v[156:159], v[196:199], v[74:77]
	v_mfma_f32_16x16x32_bf16 v[78:81], v[164:167], v[196:199], v[78:81]
	v_mfma_f32_16x16x32_bf16 v[122:125], v[160:163], v[176:179], v[122:125]
	v_mfma_f32_16x16x32_bf16 v[126:129], v[168:171], v[176:179], v[126:129]
	v_mfma_f32_16x16x32_bf16 v[106:109], v[160:163], v[184:187], v[106:109]
	v_mfma_f32_16x16x32_bf16 v[110:113], v[168:171], v[184:187], v[110:113]
	v_mfma_f32_16x16x32_bf16 v[90:93], v[160:163], v[192:195], v[90:93]
	v_mfma_f32_16x16x32_bf16 v[94:97], v[168:171], v[192:195], v[94:97]
	v_mfma_f32_16x16x32_bf16 v[74:77], v[160:163], v[200:203], v[74:77]
	v_mfma_f32_16x16x32_bf16 v[78:81], v[168:171], v[200:203], v[78:81]
	s_setprio 0
	s_barrier
	s_add_i32 s18, 0, 0x1c000
	s_add_i32 s19, s42, s22
	v_add_u32_e32 v149, s18, v1
	v_lshl_add_u64 v[230:231], v[230:231], 0, s[74:75]
	s_mov_b32 m0, s19
	ds_read_b128 v[204:207], v149
	ds_read_b128 v[208:211], v149 offset:1024
	ds_read_b128 v[212:215], v149 offset:2048
	ds_read_b128 v[226:229], v149 offset:3072
	global_load_lds_dwordx4 v[230:231], off
	v_lshl_add_u64 v[230:231], v[232:233], 0, s[74:75]
	s_add_i32 m0, s19, 0x2000
	s_nop 0
	global_load_lds_dwordx4 v[230:231], off
	s_cmp_eq_u32 s100, 0
	s_cbranch_scc1 .Lip_w6n
	s_waitcnt vmcnt(10)
	s_mov_b32 s100, 0
.Lip_w6n:
	s_barrier
	s_waitcnt lgkmcnt(0)
	s_setprio 1
	s_waitcnt lgkmcnt(0)
	v_mfma_f32_16x16x32_bf16 v[114:117], v[204:207], v[172:175], v[114:117]
	v_mfma_f32_16x16x32_bf16 v[118:121], v[212:215], v[172:175], v[118:121]
	v_mfma_f32_16x16x32_bf16 v[98:101], v[204:207], v[180:183], v[98:101]
	v_mfma_f32_16x16x32_bf16 v[102:105], v[212:215], v[180:183], v[102:105]
	v_mfma_f32_16x16x32_bf16 v[82:85], v[204:207], v[188:191], v[82:85]
	v_mfma_f32_16x16x32_bf16 v[86:89], v[212:215], v[188:191], v[86:89]
	v_mfma_f32_16x16x32_bf16 v[66:69], v[204:207], v[196:199], v[66:69]
	v_mfma_f32_16x16x32_bf16 v[70:73], v[212:215], v[196:199], v[70:73]
	v_mfma_f32_16x16x32_bf16 v[114:117], v[208:211], v[176:179], v[114:117]
	v_mfma_f32_16x16x32_bf16 v[118:121], v[226:229], v[176:179], v[118:121]
	v_mfma_f32_16x16x32_bf16 v[98:101], v[208:211], v[184:187], v[98:101]
	v_mfma_f32_16x16x32_bf16 v[102:105], v[226:229], v[184:187], v[102:105]
	v_mfma_f32_16x16x32_bf16 v[82:85], v[208:211], v[192:195], v[82:85]
	v_mfma_f32_16x16x32_bf16 v[86:89], v[226:229], v[192:195], v[86:89]
	v_mfma_f32_16x16x32_bf16 v[66:69], v[208:211], v[200:203], v[66:69]
	v_mfma_f32_16x16x32_bf16 v[70:73], v[226:229], v[200:203], v[70:73]
	s_setprio 0
	s_mov_b32 m0, s28
	v_lshl_add_u64 v[230:231], v[234:235], 0, s[74:75]
	s_barrier
	ds_read_b128 v[172:175], v151 offset:49152
	ds_read_b128 v[176:179], v151 offset:50176
	ds_read_b128 v[180:183], v151 offset:51200
	ds_read_b128 v[184:187], v151 offset:52224
	ds_read_b128 v[188:191], v151 offset:53248
	ds_read_b128 v[192:195], v151 offset:54272
	ds_read_b128 v[196:199], v151 offset:55296
	ds_read_b128 v[200:203], v151 offset:56320
	global_load_lds_dwordx4 v[230:231], off
	v_lshl_add_u64 v[230:231], v[236:237], 0, s[74:75]
	s_mov_b32 m0, s29
	s_nop 0
	global_load_lds_dwordx4 v[230:231], off
	s_barrier
	s_waitcnt lgkmcnt(0)
	s_setprio 1
	s_waitcnt lgkmcnt(0)
	v_mfma_f32_16x16x32_bf16 v[58:61], v[156:159], v[172:175], v[58:61]
	v_mfma_f32_16x16x32_bf16 v[62:65], v[164:167], v[172:175], v[62:65]
	v_mfma_f32_16x16x32_bf16 v[42:45], v[156:159], v[180:183], v[42:45]
	v_mfma_f32_16x16x32_bf16 v[46:49], v[164:167], v[180:183], v[46:49]
	v_mfma_f32_16x16x32_bf16 v[26:29], v[156:159], v[188:191], v[26:29]
	v_mfma_f32_16x16x32_bf16 v[30:33], v[164:167], v[188:191], v[30:33]
	v_mfma_f32_16x16x32_bf16 v[10:13], v[156:159], v[196:199], v[10:13]
	v_mfma_f32_16x16x32_bf16 v[14:17], v[164:167], v[196:199], v[14:17]
	v_mfma_f32_16x16x32_bf16 v[58:61], v[160:163], v[176:179], v[58:61]
	v_mfma_f32_16x16x32_bf16 v[62:65], v[168:171], v[176:179], v[62:65]
	v_mfma_f32_16x16x32_bf16 v[42:45], v[160:163], v[184:187], v[42:45]
	v_mfma_f32_16x16x32_bf16 v[46:49], v[168:171], v[184:187], v[46:49]
	v_mfma_f32_16x16x32_bf16 v[26:29], v[160:163], v[192:195], v[26:29]
	v_mfma_f32_16x16x32_bf16 v[30:33], v[168:171], v[192:195], v[30:33]
	v_mfma_f32_16x16x32_bf16 v[10:13], v[160:163], v[200:203], v[10:13]
	v_mfma_f32_16x16x32_bf16 v[14:17], v[168:171], v[200:203], v[14:17]
	s_setprio 0
	s_barrier
	s_add_u32 s16, s16, 0x40080
	s_addc_u32 s17, s17, 0
	s_add_i32 s18, s18, s22
	s_mov_b32 m0, s18
	s_nop 0
	global_load_lds_dwordx4 v134, s[16:17]
	s_add_i32 m0, s18, 0x2000
	s_nop 0
	global_load_lds_dwordx4 v130, s[16:17]
	s_waitcnt vmcnt(6)
	s_barrier
	s_setprio 1
	v_mfma_f32_16x16x32_bf16 v[50:53], v[204:207], v[172:175], v[50:53]
	v_mfma_f32_16x16x32_bf16 v[54:57], v[212:215], v[172:175], v[54:57]
	v_mfma_f32_16x16x32_bf16 v[34:37], v[204:207], v[180:183], v[34:37]
	v_mfma_f32_16x16x32_bf16 v[38:41], v[212:215], v[180:183], v[38:41]
	v_mfma_f32_16x16x32_bf16 v[18:21], v[204:207], v[188:191], v[18:21]
	v_mfma_f32_16x16x32_bf16 v[22:25], v[212:215], v[188:191], v[22:25]
	v_mfma_f32_16x16x32_bf16 v[6:9], v[204:207], v[196:199], v[6:9]
	v_mfma_f32_16x16x32_bf16 v[2:5], v[212:215], v[196:199], v[2:5]
	v_mfma_f32_16x16x32_bf16 v[50:53], v[208:211], v[176:179], v[50:53]
	v_mfma_f32_16x16x32_bf16 v[54:57], v[226:229], v[176:179], v[54:57]
	v_mfma_f32_16x16x32_bf16 v[34:37], v[208:211], v[184:187], v[34:37]
	v_mfma_f32_16x16x32_bf16 v[38:41], v[226:229], v[184:187], v[38:41]
	v_mfma_f32_16x16x32_bf16 v[18:21], v[208:211], v[192:195], v[18:21]
	v_mfma_f32_16x16x32_bf16 v[22:25], v[226:229], v[192:195], v[22:25]
	v_mfma_f32_16x16x32_bf16 v[6:9], v[208:211], v[200:203], v[6:9]
	v_mfma_f32_16x16x32_bf16 v[2:5], v[226:229], v[200:203], v[2:5]
	s_setprio 0
	s_add_u32 s14, s14, 0x100
	s_addc_u32 s15, s15, 0
	s_add_u32 s39, s39, 0x100
	s_addc_u32 s40, s40, 0
	s_cmp_ge_i32 s41, s27
	s_mov_b32 s16, s41
	s_barrier
	s_cbranch_scc0 .LBB0_239
	v_readlane_b32 s38, v255, 8
	v_mov_b32_e32 v203, v155
	v_readlane_b32 s39, v255, 9
	s_cmp_lt_i32 s35, 32
	s_mov_b64 s[14:15], -1
	s_cbranch_scc1 .LBB0_243

.LBB0_410:
	s_add_i32 s44, s20, 2
	s_add_u32 s21, s6, 0xffff0080
	s_addc_u32 s22, s7, -1
	s_add_i32 s45, 0, 0x10000
	v_add_u32_e32 v106, s45, v166
	ds_read_b128 v[86:89], v106
	ds_read_b128 v[94:97], v106 offset:1024
	ds_read_b128 v[98:101], v106 offset:2048
	ds_read_b128 v[106:109], v106 offset:3072
	s_cmp_eq_u32 s36, s20
	s_cselect_b32 s20, s41, s42
	s_cselect_b32 s23, s13, s22
	s_cselect_b32 s22, s15, s21
	s_cselect_b32 s21, s40, s43
	s_add_i32 m0, s27, 0xc000
	ds_read_b128 v[162:165], v168
	ds_read_b128 v[170:173], v168 offset:1024
	ds_read_b128 v[174:177], v168 offset:2048
	ds_read_b128 v[178:181], v168 offset:3072
	ds_read_b128 v[182:185], v168 offset:4096
	ds_read_b128 v[186:189], v168 offset:5120
	ds_read_b128 v[190:193], v168 offset:6144
	ds_read_b128 v[194:197], v168 offset:7168
	global_load_lds_dwordx4 v158, s[6:7]
	s_add_i32 m0, s27, 0xe000
	s_nop 0
	global_load_lds_dwordx4 v160, s[6:7]
	s_waitcnt lgkmcnt(8)
	s_barrier
	s_waitcnt lgkmcnt(0)
	s_setprio 1
	s_waitcnt lgkmcnt(0)
	v_mfma_f32_16x16x32_bf16 v[148:151], v[86:89], v[162:165], v[148:151]
	v_mfma_f32_16x16x32_bf16 v[138:141], v[98:101], v[162:165], v[138:141]
	v_mfma_f32_16x16x32_bf16 v[126:129], v[86:89], v[174:177], v[126:129]
	v_mfma_f32_16x16x32_bf16 v[122:125], v[98:101], v[174:177], v[122:125]
	v_mfma_f32_16x16x32_bf16 v[110:113], v[86:89], v[182:185], v[110:113]
	v_mfma_f32_16x16x32_bf16 v[102:105], v[98:101], v[182:185], v[102:105]
	v_mfma_f32_16x16x32_bf16 v[78:81], v[86:89], v[190:193], v[78:81]
	v_mfma_f32_16x16x32_bf16 v[74:77], v[98:101], v[190:193], v[74:77]
	v_mfma_f32_16x16x32_bf16 v[148:151], v[94:97], v[170:173], v[148:151]
	v_mfma_f32_16x16x32_bf16 v[138:141], v[106:109], v[170:173], v[138:141]
	v_mfma_f32_16x16x32_bf16 v[126:129], v[94:97], v[178:181], v[126:129]
	v_mfma_f32_16x16x32_bf16 v[122:125], v[106:109], v[178:181], v[122:125]
	v_mfma_f32_16x16x32_bf16 v[110:113], v[94:97], v[186:189], v[110:113]
	v_mfma_f32_16x16x32_bf16 v[102:105], v[106:109], v[186:189], v[102:105]
	v_mfma_f32_16x16x32_bf16 v[78:81], v[94:97], v[194:197], v[78:81]
	v_mfma_f32_16x16x32_bf16 v[74:77], v[106:109], v[194:197], v[74:77]
	s_setprio 0
	s_barrier
	s_add_i32 s48, 0, 0x14000
	s_add_i32 s45, s45, s26
	v_add_u32_e32 v169, s48, v166
	v_lshl_add_u64 v[214:215], s[20:21], 0, v[154:155]
	s_mov_b32 m0, s45
	ds_read_b128 v[198:201], v169
	ds_read_b128 v[202:205], v169 offset:1024
	ds_read_b128 v[206:209], v169 offset:2048
	ds_read_b128 v[210:213], v169 offset:3072
	global_load_lds_dwordx4 v[214:215], off
	v_lshl_add_u64 v[226:227], s[20:21], 0, v[142:143]
	s_add_i32 m0, s45, 0x2000
	s_nop 0
	global_load_lds_dwordx4 v[226:227], off
	s_barrier
	s_waitcnt lgkmcnt(0)
	s_setprio 1
	s_waitcnt lgkmcnt(0)
	v_mfma_f32_16x16x32_bf16 v[134:137], v[198:201], v[162:165], v[134:137]
	v_mfma_f32_16x16x32_bf16 v[130:133], v[206:209], v[162:165], v[130:133]
	v_mfma_f32_16x16x32_bf16 v[118:121], v[198:201], v[174:177], v[118:121]
	v_mfma_f32_16x16x32_bf16 v[114:117], v[206:209], v[174:177], v[114:117]
	v_mfma_f32_16x16x32_bf16 v[90:93], v[198:201], v[182:185], v[90:93]
	v_mfma_f32_16x16x32_bf16 v[82:85], v[206:209], v[182:185], v[82:85]
	v_mfma_f32_16x16x32_bf16 v[70:73], v[198:201], v[190:193], v[70:73]
	v_mfma_f32_16x16x32_bf16 v[66:69], v[206:209], v[190:193], v[66:69]
	v_mfma_f32_16x16x32_bf16 v[134:137], v[202:205], v[170:173], v[134:137]
	v_mfma_f32_16x16x32_bf16 v[130:133], v[210:213], v[170:173], v[130:133]
	v_mfma_f32_16x16x32_bf16 v[118:121], v[202:205], v[178:181], v[118:121]
	v_mfma_f32_16x16x32_bf16 v[114:117], v[210:213], v[178:181], v[114:117]
	v_mfma_f32_16x16x32_bf16 v[90:93], v[202:205], v[186:189], v[90:93]
	v_mfma_f32_16x16x32_bf16 v[82:85], v[210:213], v[186:189], v[82:85]
	v_mfma_f32_16x16x32_bf16 v[70:73], v[202:205], v[194:197], v[70:73]
	v_mfma_f32_16x16x32_bf16 v[66:69], v[210:213], v[194:197], v[66:69]
	s_setprio 0
	s_mov_b32 m0, s27
	v_lshl_add_u64 v[228:229], s[22:23], 0, v[156:157]
	s_barrier
	ds_read_b128 v[162:165], v168 offset:16384
	ds_read_b128 v[170:173], v168 offset:17408
	ds_read_b128 v[174:177], v168 offset:18432
	ds_read_b128 v[178:181], v168 offset:19456
	ds_read_b128 v[182:185], v168 offset:20480
	ds_read_b128 v[186:189], v168 offset:21504
	ds_read_b128 v[190:193], v168 offset:22528
	ds_read_b128 v[194:197], v168 offset:23552
	global_load_lds_dwordx4 v[228:229], off
	v_lshl_add_u64 v[230:231], s[22:23], 0, v[152:153]
	s_mov_b32 m0, s28
	s_nop 0
	global_load_lds_dwordx4 v[230:231], off
	s_barrier
	s_waitcnt lgkmcnt(0)
	s_setprio 1
	s_waitcnt lgkmcnt(0)
	v_mfma_f32_16x16x32_bf16 v[62:65], v[86:89], v[162:165], v[62:65]
	v_mfma_f32_16x16x32_bf16 v[58:61], v[98:101], v[162:165], v[58:61]
	v_mfma_f32_16x16x32_bf16 v[46:49], v[86:89], v[174:177], v[46:49]
	v_mfma_f32_16x16x32_bf16 v[42:45], v[98:101], v[174:177], v[42:45]
	v_mfma_f32_16x16x32_bf16 v[30:33], v[86:89], v[182:185], v[30:33]
	v_mfma_f32_16x16x32_bf16 v[26:29], v[98:101], v[182:185], v[26:29]
	v_mfma_f32_16x16x32_bf16 v[14:17], v[86:89], v[190:193], v[14:17]
	v_mfma_f32_16x16x32_bf16 v[10:13], v[98:101], v[190:193], v[10:13]
	v_mfma_f32_16x16x32_bf16 v[62:65], v[94:97], v[170:173], v[62:65]
	v_mfma_f32_16x16x32_bf16 v[58:61], v[106:109], v[170:173], v[58:61]
	v_mfma_f32_16x16x32_bf16 v[46:49], v[94:97], v[178:181], v[46:49]
	v_mfma_f32_16x16x32_bf16 v[42:45], v[106:109], v[178:181], v[42:45]
	v_mfma_f32_16x16x32_bf16 v[30:33], v[94:97], v[186:189], v[30:33]
	v_mfma_f32_16x16x32_bf16 v[26:29], v[106:109], v[186:189], v[26:29]
	v_mfma_f32_16x16x32_bf16 v[14:17], v[94:97], v[194:197], v[14:17]
	v_mfma_f32_16x16x32_bf16 v[10:13], v[106:109], v[194:197], v[10:13]
	s_setprio 0
	s_barrier
	s_add_u32 s46, s20, 0x10000
	s_addc_u32 s47, s21, 0
	s_add_i32 s45, s48, s26
	s_mov_b32 m0, s45
	s_nop 0
	global_load_lds_dwordx4 v154, s[46:47]
	s_add_i32 m0, s45, 0x2000
	s_nop 0
	global_load_lds_dwordx4 v142, s[46:47]
	s_waitcnt vmcnt(6)
	s_barrier
	s_setprio 1
	v_mfma_f32_16x16x32_bf16 v[54:57], v[198:201], v[162:165], v[54:57]
	v_mfma_f32_16x16x32_bf16 v[50:53], v[206:209], v[162:165], v[50:53]
	v_mfma_f32_16x16x32_bf16 v[38:41], v[198:201], v[174:177], v[38:41]
	v_mfma_f32_16x16x32_bf16 v[34:37], v[206:209], v[174:177], v[34:37]
	v_mfma_f32_16x16x32_bf16 v[22:25], v[198:201], v[182:185], v[22:25]
	v_mfma_f32_16x16x32_bf16 v[18:21], v[206:209], v[182:185], v[18:21]
	v_mfma_f32_16x16x32_bf16 v[6:9], v[198:201], v[190:193], v[6:9]
	v_mfma_f32_16x16x32_bf16 v[2:5], v[206:209], v[190:193], v[2:5]
	v_mfma_f32_16x16x32_bf16 v[54:57], v[202:205], v[170:173], v[54:57]
	v_mfma_f32_16x16x32_bf16 v[50:53], v[210:213], v[170:173], v[50:53]
	v_mfma_f32_16x16x32_bf16 v[38:41], v[202:205], v[178:181], v[38:41]
	v_mfma_f32_16x16x32_bf16 v[34:37], v[210:213], v[178:181], v[34:37]
	v_mfma_f32_16x16x32_bf16 v[22:25], v[202:205], v[186:189], v[22:25]
	v_mfma_f32_16x16x32_bf16 v[18:21], v[210:213], v[186:189], v[18:21]
	v_mfma_f32_16x16x32_bf16 v[6:9], v[202:205], v[194:197], v[6:9]
	v_mfma_f32_16x16x32_bf16 v[2:5], v[210:213], v[194:197], v[2:5]
	s_setprio 0
	s_add_i32 s45, 0, 0x18000
	v_add_u32_e32 v106, s45, v166
	s_barrier
	ds_read_b128 v[86:89], v106
	ds_read_b128 v[94:97], v106 offset:1024
	ds_read_b128 v[98:101], v106 offset:2048
	ds_read_b128 v[106:109], v106 offset:3072
	s_add_u32 s22, s22, 0x10000
	s_addc_u32 s23, s23, 0
	s_mov_b32 m0, s29
	ds_read_b128 v[162:165], v168 offset:32768
	ds_read_b128 v[170:173], v168 offset:33792
	ds_read_b128 v[174:177], v168 offset:34816
	ds_read_b128 v[178:181], v168 offset:35840
	ds_read_b128 v[182:185], v168 offset:36864
	ds_read_b128 v[186:189], v168 offset:37888
	ds_read_b128 v[190:193], v168 offset:38912
	ds_read_b128 v[194:197], v168 offset:39936
	global_load_lds_dwordx4 v156, s[22:23]
	s_mov_b32 m0, s30
	s_nop 0
	global_load_lds_dwordx4 v152, s[22:23]
	s_waitcnt lgkmcnt(8)
	s_barrier
	s_waitcnt lgkmcnt(0)
	s_setprio 1
	s_waitcnt lgkmcnt(0)
	v_mfma_f32_16x16x32_bf16 v[148:151], v[86:89], v[162:165], v[148:151]
	v_mfma_f32_16x16x32_bf16 v[138:141], v[98:101], v[162:165], v[138:141]
	v_mfma_f32_16x16x32_bf16 v[126:129], v[86:89], v[174:177], v[126:129]
	v_mfma_f32_16x16x32_bf16 v[122:125], v[98:101], v[174:177], v[122:125]
	v_mfma_f32_16x16x32_bf16 v[110:113], v[86:89], v[182:185], v[110:113]
	v_mfma_f32_16x16x32_bf16 v[102:105], v[98:101], v[182:185], v[102:105]
	v_mfma_f32_16x16x32_bf16 v[78:81], v[86:89], v[190:193], v[78:81]
	v_mfma_f32_16x16x32_bf16 v[74:77], v[98:101], v[190:193], v[74:77]
	v_mfma_f32_16x16x32_bf16 v[148:151], v[94:97], v[170:173], v[148:151]
	v_mfma_f32_16x16x32_bf16 v[138:141], v[106:109], v[170:173], v[138:141]
	v_mfma_f32_16x16x32_bf16 v[126:129], v[94:97], v[178:181], v[126:129]
	v_mfma_f32_16x16x32_bf16 v[122:125], v[106:109], v[178:181], v[122:125]
	v_mfma_f32_16x16x32_bf16 v[110:113], v[94:97], v[186:189], v[110:113]
	v_mfma_f32_16x16x32_bf16 v[102:105], v[106:109], v[186:189], v[102:105]
	v_mfma_f32_16x16x32_bf16 v[78:81], v[94:97], v[194:197], v[78:81]
	v_mfma_f32_16x16x32_bf16 v[74:77], v[106:109], v[194:197], v[74:77]
	s_setprio 0
	s_barrier
	s_add_i32 s22, 0, 0x1c000
	s_add_i32 s23, s45, s26
	v_add_u32_e32 v169, s22, v166
	v_lshl_add_u64 v[214:215], v[214:215], 0, s[74:75]
	s_mov_b32 m0, s23
	ds_read_b128 v[198:201], v169
	ds_read_b128 v[202:205], v169 offset:1024
	ds_read_b128 v[206:209], v169 offset:2048
	ds_read_b128 v[210:213], v169 offset:3072
	global_load_lds_dwordx4 v[214:215], off
	v_lshl_add_u64 v[214:215], v[226:227], 0, s[74:75]
	s_add_i32 m0, s23, 0x2000
	s_nop 0
	global_load_lds_dwordx4 v[214:215], off
	s_barrier
	s_waitcnt lgkmcnt(0)
	s_setprio 1
	s_waitcnt lgkmcnt(0)
	v_mfma_f32_16x16x32_bf16 v[134:137], v[198:201], v[162:165], v[134:137]
	v_mfma_f32_16x16x32_bf16 v[130:133], v[206:209], v[162:165], v[130:133]
	v_mfma_f32_16x16x32_bf16 v[118:121], v[198:201], v[174:177], v[118:121]
	v_mfma_f32_16x16x32_bf16 v[114:117], v[206:209], v[174:177], v[114:117]
	v_mfma_f32_16x16x32_bf16 v[90:93], v[198:201], v[182:185], v[90:93]
	v_mfma_f32_16x16x32_bf16 v[82:85], v[206:209], v[182:185], v[82:85]
	v_mfma_f32_16x16x32_bf16 v[70:73], v[198:201], v[190:193], v[70:73]
	v_mfma_f32_16x16x32_bf16 v[66:69], v[206:209], v[190:193], v[66:69]
	v_mfma_f32_16x16x32_bf16 v[134:137], v[202:205], v[170:173], v[134:137]
	v_mfma_f32_16x16x32_bf16 v[130:133], v[210:213], v[170:173], v[130:133]
	v_mfma_f32_16x16x32_bf16 v[118:121], v[202:205], v[178:181], v[118:121]
	v_mfma_f32_16x16x32_bf16 v[114:117], v[210:213], v[178:181], v[114:117]
	v_mfma_f32_16x16x32_bf16 v[90:93], v[202:205], v[186:189], v[90:93]
	v_mfma_f32_16x16x32_bf16 v[82:85], v[210:213], v[186:189], v[82:85]
	v_mfma_f32_16x16x32_bf16 v[70:73], v[202:205], v[194:197], v[70:73]
	v_mfma_f32_16x16x32_bf16 v[66:69], v[210:213], v[194:197], v[66:69]
	s_setprio 0
	s_mov_b32 m0, s34
	v_lshl_add_u64 v[214:215], v[228:229], 0, s[74:75]
	s_barrier
	ds_read_b128 v[162:165], v168 offset:49152
	ds_read_b128 v[170:173], v168 offset:50176
	ds_read_b128 v[174:177], v168 offset:51200
	ds_read_b128 v[178:181], v168 offset:52224
	ds_read_b128 v[182:185], v168 offset:53248
	ds_read_b128 v[186:189], v168 offset:54272
	ds_read_b128 v[190:193], v168 offset:55296
	ds_read_b128 v[194:197], v168 offset:56320
	global_load_lds_dwordx4 v[214:215], off
	v_lshl_add_u64 v[214:215], v[230:231], 0, s[74:75]
	s_mov_b32 m0, s35
	s_nop 0
	global_load_lds_dwordx4 v[214:215], off
	s_barrier
	s_waitcnt lgkmcnt(0)
	s_setprio 1
	s_waitcnt lgkmcnt(0)
	v_mfma_f32_16x16x32_bf16 v[62:65], v[86:89], v[162:165], v[62:65]
	v_mfma_f32_16x16x32_bf16 v[58:61], v[98:101], v[162:165], v[58:61]
	v_mfma_f32_16x16x32_bf16 v[46:49], v[86:89], v[174:177], v[46:49]
	v_mfma_f32_16x16x32_bf16 v[42:45], v[98:101], v[174:177], v[42:45]
	v_mfma_f32_16x16x32_bf16 v[30:33], v[86:89], v[182:185], v[30:33]
	v_mfma_f32_16x16x32_bf16 v[26:29], v[98:101], v[182:185], v[26:29]
	v_mfma_f32_16x16x32_bf16 v[14:17], v[86:89], v[190:193], v[14:17]
	v_mfma_f32_16x16x32_bf16 v[10:13], v[98:101], v[190:193], v[10:13]
	v_mfma_f32_16x16x32_bf16 v[62:65], v[94:97], v[170:173], v[62:65]
	v_mfma_f32_16x16x32_bf16 v[58:61], v[106:109], v[170:173], v[58:61]
	v_mfma_f32_16x16x32_bf16 v[46:49], v[94:97], v[178:181], v[46:49]
	v_mfma_f32_16x16x32_bf16 v[42:45], v[106:109], v[178:181], v[42:45]
	v_mfma_f32_16x16x32_bf16 v[30:33], v[94:97], v[186:189], v[30:33]
	v_mfma_f32_16x16x32_bf16 v[26:29], v[106:109], v[186:189], v[26:29]
	v_mfma_f32_16x16x32_bf16 v[14:17], v[94:97], v[194:197], v[14:17]
	v_mfma_f32_16x16x32_bf16 v[10:13], v[106:109], v[194:197], v[10:13]
	s_setprio 0
	s_barrier
	s_add_u32 s20, s20, 0x10080
	s_addc_u32 s21, s21, 0
	s_add_i32 s22, s22, s26
	s_mov_b32 m0, s22
	s_nop 0
	global_load_lds_dwordx4 v154, s[20:21]
	s_add_i32 m0, s22, 0x2000
	s_nop 0
	global_load_lds_dwordx4 v142, s[20:21]
	s_waitcnt vmcnt(6)
	s_barrier
	s_setprio 1
	v_mfma_f32_16x16x32_bf16 v[54:57], v[198:201], v[162:165], v[54:57]
	v_mfma_f32_16x16x32_bf16 v[50:53], v[206:209], v[162:165], v[50:53]
	v_mfma_f32_16x16x32_bf16 v[38:41], v[198:201], v[174:177], v[38:41]
	v_mfma_f32_16x16x32_bf16 v[34:37], v[206:209], v[174:177], v[34:37]
	v_mfma_f32_16x16x32_bf16 v[22:25], v[198:201], v[182:185], v[22:25]
	v_mfma_f32_16x16x32_bf16 v[18:21], v[206:209], v[182:185], v[18:21]
	v_mfma_f32_16x16x32_bf16 v[6:9], v[198:201], v[190:193], v[6:9]
	v_mfma_f32_16x16x32_bf16 v[2:5], v[206:209], v[190:193], v[2:5]
	v_mfma_f32_16x16x32_bf16 v[54:57], v[202:205], v[170:173], v[54:57]
	v_mfma_f32_16x16x32_bf16 v[50:53], v[210:213], v[170:173], v[50:53]
	v_mfma_f32_16x16x32_bf16 v[38:41], v[202:205], v[178:181], v[38:41]
	v_mfma_f32_16x16x32_bf16 v[34:37], v[210:213], v[178:181], v[34:37]
	v_mfma_f32_16x16x32_bf16 v[22:25], v[202:205], v[186:189], v[22:25]
	v_mfma_f32_16x16x32_bf16 v[18:21], v[210:213], v[186:189], v[18:21]
	v_mfma_f32_16x16x32_bf16 v[6:9], v[202:205], v[194:197], v[6:9]
	v_mfma_f32_16x16x32_bf16 v[2:5], v[210:213], v[194:197], v[2:5]
	s_setprio 0
	s_add_u32 s6, s6, 0x100
	s_addc_u32 s7, s7, 0
	s_add_u32 s42, s42, 0x100
	s_addc_u32 s43, s43, 0
	s_cmp_ge_i32 s44, s31
	s_mov_b32 s20, s44
	s_barrier
	s_cbranch_scc0 .LBB0_410
	v_mov_b32_e32 v203, v216

.LBB0_988:
	s_add_i32 s36, s12, 2
	s_add_u32 s10, s0, 0x100
	s_addc_u32 s11, s1, 0
	s_add_i32 s37, 0, 0x10000
	v_add_u32_e32 v102, s37, v1
	ds_read_b128 v[66:69], v102
	ds_read_b128 v[78:81], v102 offset:1024
	ds_read_b128 v[90:93], v102 offset:2048
	ds_read_b128 v[102:105], v102 offset:3072
	s_cmp_eq_u32 s31, s12
	s_cselect_b32 s12, s4, s34
	s_cselect_b32 s15, s9, s11
	s_cselect_b32 s14, s8, s10
	s_cselect_b32 s13, s5, s35
	v_lshl_add_u64 v[184:185], s[0:1], 0, v[210:211]
	s_add_i32 m0, s20, 0xc000
	ds_read_b128 v[114:117], v226
	ds_read_b128 v[126:129], v226 offset:1024
	ds_read_b128 v[138:141], v226 offset:2048
	ds_read_b128 v[156:159], v226 offset:3072
	ds_read_b128 v[160:163], v226 offset:4096
	ds_read_b128 v[164:167], v226 offset:5120
	ds_read_b128 v[176:179], v226 offset:6144
	ds_read_b128 v[180:183], v226 offset:7168
	global_load_lds_dwordx4 v[184:185], off
	v_lshl_add_u64 v[184:185], s[0:1], 0, v[212:213]
	s_add_i32 m0, s20, 0xe000
	s_nop 0
	global_load_lds_dwordx4 v[184:185], off
	s_waitcnt lgkmcnt(8)
	s_barrier
	s_waitcnt lgkmcnt(0)
	s_setprio 1
	s_waitcnt lgkmcnt(0)
	v_mfma_f32_16x16x32_bf16 v[172:175], v[66:69], v[114:117], v[172:175]
	v_mfma_f32_16x16x32_bf16 v[168:171], v[90:93], v[114:117], v[168:171]
	v_mfma_f32_16x16x32_bf16 v[134:137], v[66:69], v[138:141], v[134:137]
	v_mfma_f32_16x16x32_bf16 v[130:133], v[90:93], v[138:141], v[130:133]
	v_mfma_f32_16x16x32_bf16 v[110:113], v[66:69], v[160:163], v[110:113]
	v_mfma_f32_16x16x32_bf16 v[106:109], v[90:93], v[160:163], v[106:109]
	v_mfma_f32_16x16x32_bf16 v[86:89], v[66:69], v[176:179], v[86:89]
	v_mfma_f32_16x16x32_bf16 v[82:85], v[90:93], v[176:179], v[82:85]
	v_mfma_f32_16x16x32_bf16 v[172:175], v[78:81], v[126:129], v[172:175]
	v_mfma_f32_16x16x32_bf16 v[168:171], v[102:105], v[126:129], v[168:171]
	v_mfma_f32_16x16x32_bf16 v[134:137], v[78:81], v[156:159], v[134:137]
	v_mfma_f32_16x16x32_bf16 v[130:133], v[102:105], v[156:159], v[130:133]
	v_mfma_f32_16x16x32_bf16 v[110:113], v[78:81], v[164:167], v[110:113]
	v_mfma_f32_16x16x32_bf16 v[106:109], v[102:105], v[164:167], v[106:109]
	v_mfma_f32_16x16x32_bf16 v[86:89], v[78:81], v[180:183], v[86:89]
	v_mfma_f32_16x16x32_bf16 v[82:85], v[102:105], v[180:183], v[82:85]
	s_setprio 0
	s_barrier
	s_add_i32 s38, 0, 0x14000
	s_add_i32 s0, s37, s19
	v_add_u32_e32 v196, s38, v1
	v_lshl_add_u64 v[234:235], s[12:13], 0, v[202:203]
	s_mov_b32 m0, s0
	ds_read_b128 v[184:187], v196
	ds_read_b128 v[188:191], v196 offset:1024
	ds_read_b128 v[192:195], v196 offset:2048
	ds_read_b128 v[196:199], v196 offset:3072
	global_load_lds_dwordx4 v[234:235], off
	v_lshl_add_u64 v[236:237], s[12:13], 0, v[142:143]
	s_add_i32 m0, s0, 0x2000
	s_nop 0
	global_load_lds_dwordx4 v[236:237], off
	s_barrier
	s_waitcnt lgkmcnt(0)
	s_setprio 1
	s_waitcnt lgkmcnt(0)
	v_mfma_f32_16x16x32_bf16 v[152:155], v[184:187], v[114:117], v[152:155]
	v_mfma_f32_16x16x32_bf16 v[122:125], v[184:187], v[138:141], v[122:125]
	v_mfma_f32_16x16x32_bf16 v[118:121], v[192:195], v[138:141], v[118:121]
	v_mfma_f32_16x16x32_bf16 v[98:101], v[184:187], v[160:163], v[98:101]
	v_mfma_f32_16x16x32_bf16 v[94:97], v[192:195], v[160:163], v[94:97]
	v_mfma_f32_16x16x32_bf16 v[74:77], v[184:187], v[176:179], v[74:77]
	v_mfma_f32_16x16x32_bf16 v[70:73], v[192:195], v[176:179], v[70:73]
	v_mfma_f32_16x16x32_bf16 v[152:155], v[188:191], v[126:129], v[152:155]
	v_mfma_f32_16x16x32_bf16 v[114:117], v[192:195], v[114:117], v[148:151]
	v_mfma_f32_16x16x32_bf16 v[122:125], v[188:191], v[156:159], v[122:125]
	v_mfma_f32_16x16x32_bf16 v[118:121], v[196:199], v[156:159], v[118:121]
	v_mfma_f32_16x16x32_bf16 v[98:101], v[188:191], v[164:167], v[98:101]
	v_mfma_f32_16x16x32_bf16 v[94:97], v[196:199], v[164:167], v[94:97]
	v_mfma_f32_16x16x32_bf16 v[74:77], v[188:191], v[180:183], v[74:77]
	v_mfma_f32_16x16x32_bf16 v[70:73], v[196:199], v[180:183], v[70:73]
	v_mfma_f32_16x16x32_bf16 v[114:117], v[196:199], v[126:129], v[114:117]
	s_setprio 0
	s_mov_b32 m0, s20
	v_lshl_add_u64 v[238:239], s[14:15], 0, v[204:205]
	s_barrier
	ds_read_b128 v[126:129], v226 offset:16384
	ds_read_b128 v[138:141], v226 offset:17408
	ds_read_b128 v[148:151], v226 offset:18432
	ds_read_b128 v[156:159], v226 offset:19456
	ds_read_b128 v[160:163], v226 offset:20480
	ds_read_b128 v[164:167], v226 offset:21504
	ds_read_b128 v[176:179], v226 offset:22528
	ds_read_b128 v[180:183], v226 offset:23552
	global_load_lds_dwordx4 v[238:239], off
	v_lshl_add_u64 v[240:241], s[14:15], 0, v[200:201]
	s_mov_b32 m0, s21
	s_nop 0
	global_load_lds_dwordx4 v[240:241], off
	s_barrier
	s_waitcnt lgkmcnt(0)
	s_setprio 1
	s_waitcnt lgkmcnt(0)
	v_mfma_f32_16x16x32_bf16 v[62:65], v[66:69], v[126:129], v[62:65]
	v_mfma_f32_16x16x32_bf16 v[58:61], v[90:93], v[126:129], v[58:61]
	v_mfma_f32_16x16x32_bf16 v[46:49], v[66:69], v[148:151], v[46:49]
	v_mfma_f32_16x16x32_bf16 v[42:45], v[90:93], v[148:151], v[42:45]
	v_mfma_f32_16x16x32_bf16 v[30:33], v[66:69], v[160:163], v[30:33]
	v_mfma_f32_16x16x32_bf16 v[26:29], v[90:93], v[160:163], v[26:29]
	v_mfma_f32_16x16x32_bf16 v[14:17], v[66:69], v[176:179], v[14:17]
	v_mfma_f32_16x16x32_bf16 v[10:13], v[90:93], v[176:179], v[10:13]
	v_mfma_f32_16x16x32_bf16 v[62:65], v[78:81], v[138:141], v[62:65]
	v_mfma_f32_16x16x32_bf16 v[58:61], v[102:105], v[138:141], v[58:61]
	v_mfma_f32_16x16x32_bf16 v[46:49], v[78:81], v[156:159], v[46:49]
	v_mfma_f32_16x16x32_bf16 v[42:45], v[102:105], v[156:159], v[42:45]
	v_mfma_f32_16x16x32_bf16 v[30:33], v[78:81], v[164:167], v[30:33]
	v_mfma_f32_16x16x32_bf16 v[26:29], v[102:105], v[164:167], v[26:29]
	v_mfma_f32_16x16x32_bf16 v[14:17], v[78:81], v[180:183], v[14:17]
	v_mfma_f32_16x16x32_bf16 v[10:13], v[102:105], v[180:183], v[10:13]
	s_setprio 0
	s_barrier
	s_add_u32 s0, s12, 0xd0000
	s_addc_u32 s1, s13, 0
	s_add_i32 s37, s38, s19
	s_mov_b32 m0, s37
	s_nop 0
	global_load_lds_dwordx4 v202, s[0:1]
	s_add_i32 m0, s37, 0x2000
	s_nop 0
	global_load_lds_dwordx4 v142, s[0:1]
	s_waitcnt vmcnt(6)
	s_barrier
	s_setprio 1
	v_mfma_f32_16x16x32_bf16 v[54:57], v[184:187], v[126:129], v[54:57]
	v_mfma_f32_16x16x32_bf16 v[50:53], v[192:195], v[126:129], v[50:53]
	v_mfma_f32_16x16x32_bf16 v[38:41], v[184:187], v[148:151], v[38:41]
	v_mfma_f32_16x16x32_bf16 v[34:37], v[192:195], v[148:151], v[34:37]
	v_mfma_f32_16x16x32_bf16 v[22:25], v[184:187], v[160:163], v[22:25]
	v_mfma_f32_16x16x32_bf16 v[18:21], v[192:195], v[160:163], v[18:21]
	v_mfma_f32_16x16x32_bf16 v[6:9], v[184:187], v[176:179], v[6:9]
	v_mfma_f32_16x16x32_bf16 v[2:5], v[192:195], v[176:179], v[2:5]
	v_mfma_f32_16x16x32_bf16 v[54:57], v[188:191], v[138:141], v[54:57]
	v_mfma_f32_16x16x32_bf16 v[50:53], v[196:199], v[138:141], v[50:53]
	v_mfma_f32_16x16x32_bf16 v[38:41], v[188:191], v[156:159], v[38:41]
	v_mfma_f32_16x16x32_bf16 v[34:37], v[196:199], v[156:159], v[34:37]
	v_mfma_f32_16x16x32_bf16 v[22:25], v[188:191], v[164:167], v[22:25]
	v_mfma_f32_16x16x32_bf16 v[18:21], v[196:199], v[164:167], v[18:21]
	v_mfma_f32_16x16x32_bf16 v[6:9], v[188:191], v[180:183], v[6:9]
	v_mfma_f32_16x16x32_bf16 v[2:5], v[196:199], v[180:183], v[2:5]
	s_setprio 0
	s_add_i32 s37, 0, 0x18000
	v_add_u32_e32 v102, s37, v1
	s_barrier
	ds_read_b128 v[66:69], v102
	ds_read_b128 v[78:81], v102 offset:1024
	ds_read_b128 v[90:93], v102 offset:2048
	ds_read_b128 v[102:105], v102 offset:3072
	s_add_u32 s0, s14, 0xd0000
	s_addc_u32 s1, s15, 0
	s_mov_b32 m0, s22
	ds_read_b128 v[126:129], v226 offset:32768
	ds_read_b128 v[138:141], v226 offset:33792
	ds_read_b128 v[156:159], v226 offset:34816
	ds_read_b128 v[160:163], v226 offset:35840
	ds_read_b128 v[164:167], v226 offset:36864
	ds_read_b128 v[176:179], v226 offset:37888
	ds_read_b128 v[180:183], v226 offset:38912
	ds_read_b128 v[184:187], v226 offset:39936
	global_load_lds_dwordx4 v204, s[0:1]
	s_mov_b32 m0, s23
	s_nop 0
	global_load_lds_dwordx4 v200, s[0:1]
	s_waitcnt lgkmcnt(8)
	s_barrier
	s_waitcnt lgkmcnt(0)
	s_setprio 1
	s_waitcnt lgkmcnt(0)
	v_mfma_f32_16x16x32_bf16 v[148:151], v[66:69], v[126:129], v[172:175]
	v_mfma_f32_16x16x32_bf16 v[172:175], v[78:81], v[138:141], v[148:151]
	v_mfma_f32_16x16x32_bf16 v[148:151], v[90:93], v[126:129], v[168:171]
	v_mfma_f32_16x16x32_bf16 v[134:137], v[66:69], v[156:159], v[134:137]
	v_mfma_f32_16x16x32_bf16 v[130:133], v[90:93], v[156:159], v[130:133]
	v_mfma_f32_16x16x32_bf16 v[110:113], v[66:69], v[164:167], v[110:113]
	v_mfma_f32_16x16x32_bf16 v[106:109], v[90:93], v[164:167], v[106:109]
	v_mfma_f32_16x16x32_bf16 v[86:89], v[66:69], v[180:183], v[86:89]
	v_mfma_f32_16x16x32_bf16 v[82:85], v[90:93], v[180:183], v[82:85]
	v_mfma_f32_16x16x32_bf16 v[168:171], v[102:105], v[138:141], v[148:151]
	v_mfma_f32_16x16x32_bf16 v[134:137], v[78:81], v[160:163], v[134:137]
	v_mfma_f32_16x16x32_bf16 v[130:133], v[102:105], v[160:163], v[130:133]
	v_mfma_f32_16x16x32_bf16 v[110:113], v[78:81], v[176:179], v[110:113]
	v_mfma_f32_16x16x32_bf16 v[106:109], v[102:105], v[176:179], v[106:109]
	v_mfma_f32_16x16x32_bf16 v[86:89], v[78:81], v[184:187], v[86:89]
	v_mfma_f32_16x16x32_bf16 v[82:85], v[102:105], v[184:187], v[82:85]
	s_setprio 0
	s_barrier
	s_add_i32 s14, 0, 0x1c000
	v_add_u32_e32 v148, s14, v1
	s_add_i32 s0, s37, s19
	ds_read_b128 v[188:191], v148
	ds_read_b128 v[192:195], v148 offset:1024
	ds_read_b128 v[196:199], v148 offset:2048
	ds_read_b128 v[230:233], v148 offset:3072
	v_lshl_add_u64 v[148:149], v[234:235], 0, s[42:43]
	s_mov_b32 m0, s0
	s_nop 0
	global_load_lds_dwordx4 v[148:149], off
	v_lshl_add_u64 v[148:149], v[236:237], 0, s[42:43]
	s_add_i32 m0, s0, 0x2000
	s_nop 0
	global_load_lds_dwordx4 v[148:149], off
	s_barrier
	s_waitcnt lgkmcnt(0)
	s_setprio 1
	s_waitcnt lgkmcnt(0)
	v_mfma_f32_16x16x32_bf16 v[148:151], v[188:191], v[126:129], v[152:155]
	v_mfma_f32_16x16x32_bf16 v[114:117], v[196:199], v[126:129], v[114:117]
	v_mfma_f32_16x16x32_bf16 v[152:155], v[192:195], v[138:141], v[148:151]
	v_mfma_f32_16x16x32_bf16 v[148:151], v[230:233], v[138:141], v[114:117]
	v_mfma_f32_16x16x32_bf16 v[114:117], v[188:191], v[156:159], v[122:125]
	v_mfma_f32_16x16x32_bf16 v[122:125], v[192:195], v[160:163], v[114:117]
	v_mfma_f32_16x16x32_bf16 v[114:117], v[196:199], v[156:159], v[118:121]
	v_mfma_f32_16x16x32_bf16 v[98:101], v[188:191], v[164:167], v[98:101]
	v_mfma_f32_16x16x32_bf16 v[94:97], v[196:199], v[164:167], v[94:97]
	v_mfma_f32_16x16x32_bf16 v[74:77], v[188:191], v[180:183], v[74:77]
	v_mfma_f32_16x16x32_bf16 v[70:73], v[196:199], v[180:183], v[70:73]
	v_mfma_f32_16x16x32_bf16 v[118:121], v[230:233], v[160:163], v[114:117]
	v_mfma_f32_16x16x32_bf16 v[98:101], v[192:195], v[176:179], v[98:101]
	v_mfma_f32_16x16x32_bf16 v[94:97], v[230:233], v[176:179], v[94:97]
	v_mfma_f32_16x16x32_bf16 v[74:77], v[192:195], v[184:187], v[74:77]
	v_mfma_f32_16x16x32_bf16 v[70:73], v[230:233], v[184:187], v[70:73]
	s_setprio 0
	s_mov_b32 m0, s25
	v_lshl_add_u64 v[184:185], v[238:239], 0, s[42:43]
	s_barrier
	ds_read_b128 v[114:117], v226 offset:49152
	ds_read_b128 v[126:129], v226 offset:50176
	ds_read_b128 v[138:141], v226 offset:51200
	ds_read_b128 v[156:159], v226 offset:52224
	ds_read_b128 v[160:163], v226 offset:53248
	ds_read_b128 v[164:167], v226 offset:54272
	ds_read_b128 v[176:179], v226 offset:55296
	ds_read_b128 v[180:183], v226 offset:56320
	global_load_lds_dwordx4 v[184:185], off
	v_lshl_add_u64 v[184:185], v[240:241], 0, s[42:43]
	s_mov_b32 m0, s26
	s_nop 0
	global_load_lds_dwordx4 v[184:185], off
	s_barrier
	s_waitcnt lgkmcnt(0)
	s_setprio 1
	s_waitcnt lgkmcnt(0)
	v_mfma_f32_16x16x32_bf16 v[62:65], v[66:69], v[114:117], v[62:65]
	v_mfma_f32_16x16x32_bf16 v[58:61], v[90:93], v[114:117], v[58:61]
	v_mfma_f32_16x16x32_bf16 v[46:49], v[66:69], v[138:141], v[46:49]
	v_mfma_f32_16x16x32_bf16 v[42:45], v[90:93], v[138:141], v[42:45]
	v_mfma_f32_16x16x32_bf16 v[30:33], v[66:69], v[160:163], v[30:33]
	v_mfma_f32_16x16x32_bf16 v[26:29], v[90:93], v[160:163], v[26:29]
	v_mfma_f32_16x16x32_bf16 v[14:17], v[66:69], v[176:179], v[14:17]
	v_mfma_f32_16x16x32_bf16 v[10:13], v[90:93], v[176:179], v[10:13]
	v_mfma_f32_16x16x32_bf16 v[62:65], v[78:81], v[126:129], v[62:65]
	v_mfma_f32_16x16x32_bf16 v[58:61], v[102:105], v[126:129], v[58:61]
	v_mfma_f32_16x16x32_bf16 v[46:49], v[78:81], v[156:159], v[46:49]
	v_mfma_f32_16x16x32_bf16 v[42:45], v[102:105], v[156:159], v[42:45]
	v_mfma_f32_16x16x32_bf16 v[30:33], v[78:81], v[164:167], v[30:33]
	v_mfma_f32_16x16x32_bf16 v[26:29], v[102:105], v[164:167], v[26:29]
	v_mfma_f32_16x16x32_bf16 v[14:17], v[78:81], v[180:183], v[14:17]
	v_mfma_f32_16x16x32_bf16 v[10:13], v[102:105], v[180:183], v[10:13]
	s_setprio 0
	s_barrier
	s_add_u32 s0, s12, 0xd0080
	s_addc_u32 s1, s13, 0
	s_add_i32 s12, s14, s19
	s_mov_b32 m0, s12
	s_nop 0
	global_load_lds_dwordx4 v202, s[0:1]
	s_add_i32 m0, s12, 0x2000
	s_nop 0
	global_load_lds_dwordx4 v142, s[0:1]
	s_waitcnt vmcnt(6)
	s_barrier
	s_setprio 1
	v_mfma_f32_16x16x32_bf16 v[54:57], v[188:191], v[114:117], v[54:57]
	v_mfma_f32_16x16x32_bf16 v[50:53], v[196:199], v[114:117], v[50:53]
	v_mfma_f32_16x16x32_bf16 v[38:41], v[188:191], v[138:141], v[38:41]
	v_mfma_f32_16x16x32_bf16 v[34:37], v[196:199], v[138:141], v[34:37]
	v_mfma_f32_16x16x32_bf16 v[22:25], v[188:191], v[160:163], v[22:25]
	v_mfma_f32_16x16x32_bf16 v[18:21], v[196:199], v[160:163], v[18:21]
	v_mfma_f32_16x16x32_bf16 v[6:9], v[188:191], v[176:179], v[6:9]
	v_mfma_f32_16x16x32_bf16 v[2:5], v[196:199], v[176:179], v[2:5]
	v_mfma_f32_16x16x32_bf16 v[54:57], v[192:195], v[126:129], v[54:57]
	v_mfma_f32_16x16x32_bf16 v[50:53], v[230:233], v[126:129], v[50:53]
	v_mfma_f32_16x16x32_bf16 v[38:41], v[192:195], v[156:159], v[38:41]
	v_mfma_f32_16x16x32_bf16 v[34:37], v[230:233], v[156:159], v[34:37]
	v_mfma_f32_16x16x32_bf16 v[22:25], v[192:195], v[164:167], v[22:25]
	v_mfma_f32_16x16x32_bf16 v[18:21], v[230:233], v[164:167], v[18:21]
	v_mfma_f32_16x16x32_bf16 v[6:9], v[192:195], v[180:183], v[6:9]
	v_mfma_f32_16x16x32_bf16 v[2:5], v[230:233], v[180:183], v[2:5]
	s_setprio 0
	s_add_u32 s34, s34, 0x100
	s_addc_u32 s35, s35, 0
	s_cmp_ge_i32 s36, s3
	s_mov_b64 s[0:1], s[10:11]
	s_mov_b32 s12, s36
	s_barrier
	s_cbranch_scc0 .LBB0_988
	v_readlane_b32 s38, v255, 8
	v_readlane_b32 s39, v255, 9
	v_readlane_b32 s35, v255, 10
	s_mov_b32 s37, s41
	s_branch .LBB0_993

.LBB0_1067:
	s_add_i32 s40, s16, 2
	s_add_u32 s17, s6, 0xfffc0080
	s_addc_u32 s18, s7, -1
	s_add_i32 s41, 0, 0x10000
	v_add_u32_e32 v148, s41, v184
	ds_read_b128 v[130:133], v148
	ds_read_b128 v[134:137], v148 offset:1024
	ds_read_b128 v[138:141], v148 offset:2048
	ds_read_b128 v[148:151], v148 offset:3072
	s_cmp_eq_u32 s30, s16
	s_cselect_b32 s16, s37, s38
	s_cselect_b32 s19, s9, s18
	s_cselect_b32 s18, s11, s17
	s_cselect_b32 s17, s36, s39
	s_add_i32 m0, s23, 0xc000
	ds_read_b128 v[152:155], v186
	ds_read_b128 v[156:159], v186 offset:1024
	ds_read_b128 v[160:163], v186 offset:2048
	ds_read_b128 v[174:177], v186 offset:3072
	ds_read_b128 v[178:181], v186 offset:4096
	ds_read_b128 v[188:191], v186 offset:5120
	ds_read_b128 v[192:195], v186 offset:6144
	ds_read_b128 v[196:199], v186 offset:7168
	global_load_lds_dwordx4 v170, s[6:7]
	s_add_i32 m0, s23, 0xe000
	s_nop 0
	global_load_lds_dwordx4 v172, s[6:7]
	s_waitcnt lgkmcnt(8)
	s_barrier
	s_waitcnt lgkmcnt(0)
	s_setprio 1
	s_waitcnt lgkmcnt(0)
	v_mfma_f32_16x16x32_bf16 v[126:129], v[130:133], v[152:155], v[126:129]
	v_mfma_f32_16x16x32_bf16 v[122:125], v[138:141], v[152:155], v[122:125]
	v_mfma_f32_16x16x32_bf16 v[110:113], v[130:133], v[160:163], v[110:113]
	v_mfma_f32_16x16x32_bf16 v[106:109], v[138:141], v[160:163], v[106:109]
	v_mfma_f32_16x16x32_bf16 v[94:97], v[130:133], v[178:181], v[94:97]
	v_mfma_f32_16x16x32_bf16 v[90:93], v[138:141], v[178:181], v[90:93]
	v_mfma_f32_16x16x32_bf16 v[78:81], v[130:133], v[192:195], v[78:81]
	v_mfma_f32_16x16x32_bf16 v[74:77], v[138:141], v[192:195], v[74:77]
	v_mfma_f32_16x16x32_bf16 v[126:129], v[134:137], v[156:159], v[126:129]
	v_mfma_f32_16x16x32_bf16 v[122:125], v[148:151], v[156:159], v[122:125]
	v_mfma_f32_16x16x32_bf16 v[110:113], v[134:137], v[174:177], v[110:113]
	v_mfma_f32_16x16x32_bf16 v[106:109], v[148:151], v[174:177], v[106:109]
	v_mfma_f32_16x16x32_bf16 v[94:97], v[134:137], v[188:191], v[94:97]
	v_mfma_f32_16x16x32_bf16 v[90:93], v[148:151], v[188:191], v[90:93]
	v_mfma_f32_16x16x32_bf16 v[78:81], v[134:137], v[196:199], v[78:81]
	v_mfma_f32_16x16x32_bf16 v[74:77], v[148:151], v[196:199], v[74:77]
	s_setprio 0
	s_barrier
	s_add_i32 s44, 0, 0x14000
	v_add_u32_e32 v182, s44, v184
	s_add_i32 s41, s41, s22
	ds_read_b128 v[200:203], v182
	ds_read_b128 v[204:207], v182 offset:1024
	ds_read_b128 v[208:211], v182 offset:2048
	ds_read_b128 v[212:215], v182 offset:3072
	v_lshl_add_u64 v[182:183], s[16:17], 0, v[166:167]
	s_mov_b32 m0, s41
	v_lshl_add_u64 v[226:227], s[16:17], 0, v[142:143]
	global_load_lds_dwordx4 v[182:183], off
	s_add_i32 m0, s41, 0x2000
	s_nop 0
	global_load_lds_dwordx4 v[226:227], off
	s_barrier
	s_waitcnt lgkmcnt(0)
	s_setprio 1
	s_waitcnt lgkmcnt(0)
	v_mfma_f32_16x16x32_bf16 v[118:121], v[200:203], v[152:155], v[118:121]
	v_mfma_f32_16x16x32_bf16 v[114:117], v[208:211], v[152:155], v[114:117]
	v_mfma_f32_16x16x32_bf16 v[102:105], v[200:203], v[160:163], v[102:105]
	v_mfma_f32_16x16x32_bf16 v[98:101], v[208:211], v[160:163], v[98:101]
	v_mfma_f32_16x16x32_bf16 v[86:89], v[200:203], v[178:181], v[86:89]
	v_mfma_f32_16x16x32_bf16 v[82:85], v[208:211], v[178:181], v[82:85]
	v_mfma_f32_16x16x32_bf16 v[70:73], v[200:203], v[192:195], v[70:73]
	v_mfma_f32_16x16x32_bf16 v[66:69], v[208:211], v[192:195], v[66:69]
	v_mfma_f32_16x16x32_bf16 v[118:121], v[204:207], v[156:159], v[118:121]
	v_mfma_f32_16x16x32_bf16 v[114:117], v[212:215], v[156:159], v[114:117]
	v_mfma_f32_16x16x32_bf16 v[102:105], v[204:207], v[174:177], v[102:105]
	v_mfma_f32_16x16x32_bf16 v[98:101], v[212:215], v[174:177], v[98:101]
	v_mfma_f32_16x16x32_bf16 v[86:89], v[204:207], v[188:191], v[86:89]
	v_mfma_f32_16x16x32_bf16 v[82:85], v[212:215], v[188:191], v[82:85]
	v_mfma_f32_16x16x32_bf16 v[70:73], v[204:207], v[196:199], v[70:73]
	v_mfma_f32_16x16x32_bf16 v[66:69], v[212:215], v[196:199], v[66:69]
	s_setprio 0
	s_mov_b32 m0, s23
	v_lshl_add_u64 v[228:229], s[18:19], 0, v[168:169]
	s_barrier
	ds_read_b128 v[152:155], v186 offset:16384
	ds_read_b128 v[156:159], v186 offset:17408
	ds_read_b128 v[160:163], v186 offset:18432
	ds_read_b128 v[174:177], v186 offset:19456
	ds_read_b128 v[178:181], v186 offset:20480
	ds_read_b128 v[188:191], v186 offset:21504
	ds_read_b128 v[192:195], v186 offset:22528
	ds_read_b128 v[196:199], v186 offset:23552
	global_load_lds_dwordx4 v[228:229], off
	v_lshl_add_u64 v[230:231], s[18:19], 0, v[164:165]
	s_mov_b32 m0, s24
	s_nop 0
	global_load_lds_dwordx4 v[230:231], off
	s_barrier
	s_waitcnt lgkmcnt(0)
	s_setprio 1
	s_waitcnt lgkmcnt(0)
	v_mfma_f32_16x16x32_bf16 v[62:65], v[130:133], v[152:155], v[62:65]
	v_mfma_f32_16x16x32_bf16 v[58:61], v[138:141], v[152:155], v[58:61]
	v_mfma_f32_16x16x32_bf16 v[46:49], v[130:133], v[160:163], v[46:49]
	v_mfma_f32_16x16x32_bf16 v[42:45], v[138:141], v[160:163], v[42:45]
	v_mfma_f32_16x16x32_bf16 v[30:33], v[130:133], v[178:181], v[30:33]
	v_mfma_f32_16x16x32_bf16 v[26:29], v[138:141], v[178:181], v[26:29]
	v_mfma_f32_16x16x32_bf16 v[14:17], v[130:133], v[192:195], v[14:17]
	v_mfma_f32_16x16x32_bf16 v[10:13], v[138:141], v[192:195], v[10:13]
	v_mfma_f32_16x16x32_bf16 v[62:65], v[134:137], v[156:159], v[62:65]
	v_mfma_f32_16x16x32_bf16 v[58:61], v[148:151], v[156:159], v[58:61]
	v_mfma_f32_16x16x32_bf16 v[46:49], v[134:137], v[174:177], v[46:49]
	v_mfma_f32_16x16x32_bf16 v[42:45], v[148:151], v[174:177], v[42:45]
	v_mfma_f32_16x16x32_bf16 v[30:33], v[134:137], v[188:191], v[30:33]
	v_mfma_f32_16x16x32_bf16 v[26:29], v[148:151], v[188:191], v[26:29]
	v_mfma_f32_16x16x32_bf16 v[14:17], v[134:137], v[196:199], v[14:17]
	v_mfma_f32_16x16x32_bf16 v[10:13], v[148:151], v[196:199], v[10:13]
	s_setprio 0
	s_barrier
	s_add_u32 s42, s16, 0x40000
	s_addc_u32 s43, s17, 0
	s_add_i32 s41, s44, s22
	s_mov_b32 m0, s41
	s_nop 0
	global_load_lds_dwordx4 v166, s[42:43]
	s_add_i32 m0, s41, 0x2000
	s_nop 0
	global_load_lds_dwordx4 v142, s[42:43]
	s_waitcnt vmcnt(6)
	s_barrier
	s_setprio 1
	v_mfma_f32_16x16x32_bf16 v[54:57], v[200:203], v[152:155], v[54:57]
	v_mfma_f32_16x16x32_bf16 v[50:53], v[208:211], v[152:155], v[50:53]
	v_mfma_f32_16x16x32_bf16 v[38:41], v[200:203], v[160:163], v[38:41]
	v_mfma_f32_16x16x32_bf16 v[34:37], v[208:211], v[160:163], v[34:37]
	v_mfma_f32_16x16x32_bf16 v[22:25], v[200:203], v[178:181], v[22:25]
	v_mfma_f32_16x16x32_bf16 v[18:21], v[208:211], v[178:181], v[18:21]
	v_mfma_f32_16x16x32_bf16 v[6:9], v[200:203], v[192:195], v[6:9]
	v_mfma_f32_16x16x32_bf16 v[2:5], v[208:211], v[192:195], v[2:5]
	v_mfma_f32_16x16x32_bf16 v[54:57], v[204:207], v[156:159], v[54:57]
	v_mfma_f32_16x16x32_bf16 v[50:53], v[212:215], v[156:159], v[50:53]
	v_mfma_f32_16x16x32_bf16 v[38:41], v[204:207], v[174:177], v[38:41]
	v_mfma_f32_16x16x32_bf16 v[34:37], v[212:215], v[174:177], v[34:37]
	v_mfma_f32_16x16x32_bf16 v[22:25], v[204:207], v[188:191], v[22:25]
	v_mfma_f32_16x16x32_bf16 v[18:21], v[212:215], v[188:191], v[18:21]
	v_mfma_f32_16x16x32_bf16 v[6:9], v[204:207], v[196:199], v[6:9]
	v_mfma_f32_16x16x32_bf16 v[2:5], v[212:215], v[196:199], v[2:5]
	s_setprio 0
	s_add_i32 s41, 0, 0x18000
	v_add_u32_e32 v148, s41, v184
	s_barrier
	ds_read_b128 v[130:133], v148
	ds_read_b128 v[134:137], v148 offset:1024
	ds_read_b128 v[138:141], v148 offset:2048
	ds_read_b128 v[148:151], v148 offset:3072
	s_add_u32 s18, s18, 0x40000
	s_addc_u32 s19, s19, 0
	s_mov_b32 m0, s25
	ds_read_b128 v[152:155], v186 offset:32768
	ds_read_b128 v[156:159], v186 offset:33792
	ds_read_b128 v[160:163], v186 offset:34816
	ds_read_b128 v[174:177], v186 offset:35840
	ds_read_b128 v[178:181], v186 offset:36864
	ds_read_b128 v[188:191], v186 offset:37888
	ds_read_b128 v[192:195], v186 offset:38912
	ds_read_b128 v[196:199], v186 offset:39936
	global_load_lds_dwordx4 v168, s[18:19]
	s_mov_b32 m0, s26
	s_nop 0
	global_load_lds_dwordx4 v164, s[18:19]
	s_waitcnt lgkmcnt(8)
	s_barrier
	s_waitcnt lgkmcnt(0)
	s_setprio 1
	s_waitcnt lgkmcnt(0)
	v_mfma_f32_16x16x32_bf16 v[126:129], v[130:133], v[152:155], v[126:129]
	v_mfma_f32_16x16x32_bf16 v[122:125], v[138:141], v[152:155], v[122:125]
	v_mfma_f32_16x16x32_bf16 v[110:113], v[130:133], v[160:163], v[110:113]
	v_mfma_f32_16x16x32_bf16 v[106:109], v[138:141], v[160:163], v[106:109]
	v_mfma_f32_16x16x32_bf16 v[94:97], v[130:133], v[178:181], v[94:97]
	v_mfma_f32_16x16x32_bf16 v[90:93], v[138:141], v[178:181], v[90:93]
	v_mfma_f32_16x16x32_bf16 v[78:81], v[130:133], v[192:195], v[78:81]
	v_mfma_f32_16x16x32_bf16 v[74:77], v[138:141], v[192:195], v[74:77]
	v_mfma_f32_16x16x32_bf16 v[126:129], v[134:137], v[156:159], v[126:129]
	v_mfma_f32_16x16x32_bf16 v[122:125], v[148:151], v[156:159], v[122:125]
	v_mfma_f32_16x16x32_bf16 v[110:113], v[134:137], v[174:177], v[110:113]
	v_mfma_f32_16x16x32_bf16 v[106:109], v[148:151], v[174:177], v[106:109]
	v_mfma_f32_16x16x32_bf16 v[94:97], v[134:137], v[188:191], v[94:97]
	v_mfma_f32_16x16x32_bf16 v[90:93], v[148:151], v[188:191], v[90:93]
	v_mfma_f32_16x16x32_bf16 v[78:81], v[134:137], v[196:199], v[78:81]
	v_mfma_f32_16x16x32_bf16 v[74:77], v[148:151], v[196:199], v[74:77]
	s_setprio 0
	s_barrier
	s_add_i32 s18, 0, 0x1c000
	s_add_i32 s19, s41, s22
	v_add_u32_e32 v187, s18, v184
	v_lshl_add_u64 v[182:183], v[182:183], 0, s[46:47]
	s_mov_b32 m0, s19
	ds_read_b128 v[200:203], v187
	ds_read_b128 v[204:207], v187 offset:1024
	ds_read_b128 v[208:211], v187 offset:2048
	ds_read_b128 v[212:215], v187 offset:3072
	global_load_lds_dwordx4 v[182:183], off
	v_lshl_add_u64 v[182:183], v[226:227], 0, s[46:47]
	s_add_i32 m0, s19, 0x2000
	s_nop 0
	global_load_lds_dwordx4 v[182:183], off
	s_barrier
	s_waitcnt lgkmcnt(0)
	s_setprio 1
	s_waitcnt lgkmcnt(0)
	v_mfma_f32_16x16x32_bf16 v[118:121], v[200:203], v[152:155], v[118:121]
	v_mfma_f32_16x16x32_bf16 v[114:117], v[208:211], v[152:155], v[114:117]
	v_mfma_f32_16x16x32_bf16 v[102:105], v[200:203], v[160:163], v[102:105]
	v_mfma_f32_16x16x32_bf16 v[98:101], v[208:211], v[160:163], v[98:101]
	v_mfma_f32_16x16x32_bf16 v[86:89], v[200:203], v[178:181], v[86:89]
	v_mfma_f32_16x16x32_bf16 v[82:85], v[208:211], v[178:181], v[82:85]
	v_mfma_f32_16x16x32_bf16 v[70:73], v[200:203], v[192:195], v[70:73]
	v_mfma_f32_16x16x32_bf16 v[66:69], v[208:211], v[192:195], v[66:69]
	v_mfma_f32_16x16x32_bf16 v[118:121], v[204:207], v[156:159], v[118:121]
	v_mfma_f32_16x16x32_bf16 v[114:117], v[212:215], v[156:159], v[114:117]
	v_mfma_f32_16x16x32_bf16 v[102:105], v[204:207], v[174:177], v[102:105]
	v_mfma_f32_16x16x32_bf16 v[98:101], v[212:215], v[174:177], v[98:101]
	v_mfma_f32_16x16x32_bf16 v[86:89], v[204:207], v[188:191], v[86:89]
	v_mfma_f32_16x16x32_bf16 v[82:85], v[212:215], v[188:191], v[82:85]
	v_mfma_f32_16x16x32_bf16 v[70:73], v[204:207], v[196:199], v[70:73]
	v_mfma_f32_16x16x32_bf16 v[66:69], v[212:215], v[196:199], v[66:69]
	s_setprio 0
	s_mov_b32 m0, s28
	v_lshl_add_u64 v[182:183], v[228:229], 0, s[46:47]
	s_barrier
	ds_read_b128 v[152:155], v186 offset:49152
	ds_read_b128 v[156:159], v186 offset:50176
	ds_read_b128 v[160:163], v186 offset:51200
	ds_read_b128 v[174:177], v186 offset:52224
	ds_read_b128 v[178:181], v186 offset:53248
	ds_read_b128 v[188:191], v186 offset:54272
	ds_read_b128 v[192:195], v186 offset:55296
	ds_read_b128 v[196:199], v186 offset:56320
	global_load_lds_dwordx4 v[182:183], off
	v_lshl_add_u64 v[182:183], v[230:231], 0, s[46:47]
	s_mov_b32 m0, s29
	s_nop 0
	global_load_lds_dwordx4 v[182:183], off
	s_barrier
	s_waitcnt lgkmcnt(0)
	s_setprio 1
	s_waitcnt lgkmcnt(0)
	v_mfma_f32_16x16x32_bf16 v[62:65], v[130:133], v[152:155], v[62:65]
	v_mfma_f32_16x16x32_bf16 v[58:61], v[138:141], v[152:155], v[58:61]
	v_mfma_f32_16x16x32_bf16 v[46:49], v[130:133], v[160:163], v[46:49]
	v_mfma_f32_16x16x32_bf16 v[42:45], v[138:141], v[160:163], v[42:45]
	v_mfma_f32_16x16x32_bf16 v[30:33], v[130:133], v[178:181], v[30:33]
	v_mfma_f32_16x16x32_bf16 v[26:29], v[138:141], v[178:181], v[26:29]
	v_mfma_f32_16x16x32_bf16 v[14:17], v[130:133], v[192:195], v[14:17]
	v_mfma_f32_16x16x32_bf16 v[10:13], v[138:141], v[192:195], v[10:13]
	v_mfma_f32_16x16x32_bf16 v[62:65], v[134:137], v[156:159], v[62:65]
	v_mfma_f32_16x16x32_bf16 v[58:61], v[148:151], v[156:159], v[58:61]
	v_mfma_f32_16x16x32_bf16 v[46:49], v[134:137], v[174:177], v[46:49]
	v_mfma_f32_16x16x32_bf16 v[42:45], v[148:151], v[174:177], v[42:45]
	v_mfma_f32_16x16x32_bf16 v[30:33], v[134:137], v[188:191], v[30:33]
	v_mfma_f32_16x16x32_bf16 v[26:29], v[148:151], v[188:191], v[26:29]
	v_mfma_f32_16x16x32_bf16 v[14:17], v[134:137], v[196:199], v[14:17]
	v_mfma_f32_16x16x32_bf16 v[10:13], v[148:151], v[196:199], v[10:13]
	s_setprio 0
	s_barrier
	s_add_u32 s16, s16, 0x40080
	s_addc_u32 s17, s17, 0
	s_add_i32 s18, s18, s22
	s_mov_b32 m0, s18
	s_nop 0
	global_load_lds_dwordx4 v166, s[16:17]
	s_add_i32 m0, s18, 0x2000
	s_nop 0
	global_load_lds_dwordx4 v142, s[16:17]
	s_waitcnt vmcnt(6)
	s_barrier
	s_setprio 1
	v_mfma_f32_16x16x32_bf16 v[54:57], v[200:203], v[152:155], v[54:57]
	v_mfma_f32_16x16x32_bf16 v[50:53], v[208:211], v[152:155], v[50:53]
	v_mfma_f32_16x16x32_bf16 v[38:41], v[200:203], v[160:163], v[38:41]
	v_mfma_f32_16x16x32_bf16 v[34:37], v[208:211], v[160:163], v[34:37]
	v_mfma_f32_16x16x32_bf16 v[22:25], v[200:203], v[178:181], v[22:25]
	v_mfma_f32_16x16x32_bf16 v[18:21], v[208:211], v[178:181], v[18:21]
	v_mfma_f32_16x16x32_bf16 v[6:9], v[200:203], v[192:195], v[6:9]
	v_mfma_f32_16x16x32_bf16 v[2:5], v[208:211], v[192:195], v[2:5]
	v_mfma_f32_16x16x32_bf16 v[54:57], v[204:207], v[156:159], v[54:57]
	v_mfma_f32_16x16x32_bf16 v[50:53], v[212:215], v[156:159], v[50:53]
	v_mfma_f32_16x16x32_bf16 v[38:41], v[204:207], v[174:177], v[38:41]
	v_mfma_f32_16x16x32_bf16 v[34:37], v[212:215], v[174:177], v[34:37]
	v_mfma_f32_16x16x32_bf16 v[22:25], v[204:207], v[188:191], v[22:25]
	v_mfma_f32_16x16x32_bf16 v[18:21], v[212:215], v[188:191], v[18:21]
	v_mfma_f32_16x16x32_bf16 v[6:9], v[204:207], v[196:199], v[6:9]
	v_mfma_f32_16x16x32_bf16 v[2:5], v[212:215], v[196:199], v[2:5]
	s_setprio 0
	s_add_u32 s6, s6, 0x100
	s_addc_u32 s7, s7, 0
	s_add_u32 s38, s38, 0x100
	s_addc_u32 s39, s39, 0
	s_cmp_ge_i32 s40, s27
	s_mov_b32 s16, s40
	s_barrier
	s_cbranch_scc0 .LBB0_1067
	v_readlane_b32 s38, v255, 8
	s_mov_b32 s37, s45
	v_readlane_b32 s39, v255, 9
	s_branch .LBB0_1058

.LBB0_1281:
	s_add_i32 s40, s16, 2
	s_add_u32 s17, s14, 0xfffe0080
	s_addc_u32 s18, s15, -1
	s_add_i32 s41, 0, 0x10000
	v_add_u32_e32 v14, s41, v170
	ds_read_b128 v[2:5], v14
	ds_read_b128 v[6:9], v14 offset:1024
	ds_read_b128 v[10:13], v14 offset:2048
	ds_read_b128 v[14:17], v14 offset:3072
	s_cmp_eq_u32 s30, s16
	s_cselect_b32 s16, s37, s38
	s_cselect_b32 s19, s5, s18
	s_cselect_b32 s18, s7, s17
	s_cselect_b32 s17, s36, s39
	s_add_i32 m0, s23, 0xc000
	ds_read_b128 v[174:177], v172
	ds_read_b128 v[178:181], v172 offset:1024
	ds_read_b128 v[182:185], v172 offset:2048
	ds_read_b128 v[186:189], v172 offset:3072
	ds_read_b128 v[190:193], v172 offset:4096
	ds_read_b128 v[194:197], v172 offset:5120
	ds_read_b128 v[198:201], v172 offset:6144
	ds_read_b128 v[202:205], v172 offset:7168
	global_load_lds_dwordx4 v158, s[14:15]
	s_add_i32 m0, s23, 0xe000
	s_nop 0
	global_load_lds_dwordx4 v160, s[14:15]
	s_waitcnt lgkmcnt(8)
	s_barrier
	s_waitcnt lgkmcnt(0)
	s_setprio 1
	s_waitcnt lgkmcnt(0)
	v_mfma_scale_f32_16x16x128_f8f6f4 v[148:151], v[2:9], v[174:181], v[148:151], v219, v220 op_sel_hi:[0,0,0]
	v_mfma_scale_f32_16x16x128_f8f6f4 v[134:137], v[10:17], v[174:181], v[134:137], v219, v220 op_sel_hi:[0,0,0]
	v_mfma_scale_f32_16x16x128_f8f6f4 v[126:129], v[2:9], v[182:189], v[126:129], v219, v220 op_sel_hi:[0,0,0]
	v_mfma_scale_f32_16x16x128_f8f6f4 v[118:121], v[10:17], v[182:189], v[118:121], v219, v220 op_sel_hi:[0,0,0]
	v_mfma_scale_f32_16x16x128_f8f6f4 v[110:113], v[2:9], v[190:197], v[110:113], v219, v220 op_sel_hi:[0,0,0]
	v_mfma_scale_f32_16x16x128_f8f6f4 v[102:105], v[10:17], v[190:197], v[102:105], v219, v220 op_sel_hi:[0,0,0]
	v_mfma_scale_f32_16x16x128_f8f6f4 v[94:97], v[2:9], v[198:205], v[94:97], v219, v220 op_sel_hi:[0,0,0]
	v_mfma_scale_f32_16x16x128_f8f6f4 v[86:89], v[10:17], v[198:205], v[86:89], v219, v220 op_sel_hi:[0,0,0]
	s_setprio 0
	s_barrier
	s_add_i32 s44, 0, 0x14000
	v_add_u32_e32 v162, s44, v170
	s_add_i32 s41, s41, s22
	ds_read_b128 v[206:209], v162
	ds_read_b128 v[210:213], v162 offset:1024
	ds_read_b128 v[226:229], v162 offset:2048
	ds_read_b128 v[230:233], v162 offset:3072
	v_lshl_add_u64 v[162:163], s[16:17], 0, v[154:155]
	s_mov_b32 m0, s41
	v_lshl_add_u64 v[164:165], s[16:17], 0, v[142:143]
	global_load_lds_dwordx4 v[162:163], off
	s_add_i32 m0, s41, 0x2000
	s_nop 0
	global_load_lds_dwordx4 v[164:165], off
	s_barrier
	s_waitcnt lgkmcnt(0)
	s_setprio 1
	s_waitcnt lgkmcnt(0)
	v_mfma_scale_f32_16x16x128_f8f6f4 v[138:141], v[206:213], v[174:181], v[138:141], v219, v220 op_sel_hi:[0,0,0]
	v_mfma_scale_f32_16x16x128_f8f6f4 v[130:133], v[226:233], v[174:181], v[130:133], v219, v220 op_sel_hi:[0,0,0]
	v_mfma_scale_f32_16x16x128_f8f6f4 v[122:125], v[206:213], v[182:189], v[122:125], v219, v220 op_sel_hi:[0,0,0]
	v_mfma_scale_f32_16x16x128_f8f6f4 v[114:117], v[226:233], v[182:189], v[114:117], v219, v220 op_sel_hi:[0,0,0]
	v_mfma_scale_f32_16x16x128_f8f6f4 v[106:109], v[206:213], v[190:197], v[106:109], v219, v220 op_sel_hi:[0,0,0]
	v_mfma_scale_f32_16x16x128_f8f6f4 v[98:101], v[226:233], v[190:197], v[98:101], v219, v220 op_sel_hi:[0,0,0]
	v_mfma_scale_f32_16x16x128_f8f6f4 v[90:93], v[206:213], v[198:205], v[90:93], v219, v220 op_sel_hi:[0,0,0]
	v_mfma_scale_f32_16x16x128_f8f6f4 v[82:85], v[226:233], v[198:205], v[82:85], v219, v220 op_sel_hi:[0,0,0]
	s_setprio 0
	s_mov_b32 m0, s23
	v_lshl_add_u64 v[166:167], s[18:19], 0, v[156:157]
	s_barrier
	ds_read_b128 v[174:177], v172 offset:16384
	ds_read_b128 v[178:181], v172 offset:17408
	ds_read_b128 v[182:185], v172 offset:18432
	ds_read_b128 v[186:189], v172 offset:19456
	ds_read_b128 v[190:193], v172 offset:20480
	ds_read_b128 v[194:197], v172 offset:21504
	ds_read_b128 v[198:201], v172 offset:22528
	ds_read_b128 v[202:205], v172 offset:23552
	global_load_lds_dwordx4 v[166:167], off
	v_lshl_add_u64 v[168:169], s[18:19], 0, v[152:153]
	s_mov_b32 m0, s24
	s_nop 0
	global_load_lds_dwordx4 v[168:169], off
	s_barrier
	s_waitcnt lgkmcnt(0)
	s_setprio 1
	s_waitcnt lgkmcnt(0)
	v_mfma_scale_f32_16x16x128_f8f6f4 v[78:81], v[2:9], v[174:181], v[78:81], v219, v220 op_sel_hi:[0,0,0]
	v_mfma_scale_f32_16x16x128_f8f6f4 v[70:73], v[10:17], v[174:181], v[70:73], v219, v220 op_sel_hi:[0,0,0]
	v_mfma_scale_f32_16x16x128_f8f6f4 v[62:65], v[2:9], v[182:189], v[62:65], v219, v220 op_sel_hi:[0,0,0]
	v_mfma_scale_f32_16x16x128_f8f6f4 v[54:57], v[10:17], v[182:189], v[54:57], v219, v220 op_sel_hi:[0,0,0]
	v_mfma_scale_f32_16x16x128_f8f6f4 v[46:49], v[2:9], v[190:197], v[46:49], v219, v220 op_sel_hi:[0,0,0]
	v_mfma_scale_f32_16x16x128_f8f6f4 v[38:41], v[10:17], v[190:197], v[38:41], v219, v220 op_sel_hi:[0,0,0]
	v_mfma_scale_f32_16x16x128_f8f6f4 v[30:33], v[2:9], v[198:205], v[30:33], v219, v220 op_sel_hi:[0,0,0]
	v_mfma_scale_f32_16x16x128_f8f6f4 v[22:25], v[10:17], v[198:205], v[22:25], v219, v220 op_sel_hi:[0,0,0]
	s_setprio 0
	s_barrier
	s_add_u32 s42, s16, 0x20000
	s_addc_u32 s43, s17, 0
	s_add_i32 s41, s44, s22
	s_mov_b32 m0, s41
	s_nop 0
	global_load_lds_dwordx4 v154, s[42:43]
	s_add_i32 m0, s41, 0x2000
	s_nop 0
	global_load_lds_dwordx4 v142, s[42:43]
	s_waitcnt vmcnt(6)
	s_barrier
	s_setprio 1
	v_mfma_scale_f32_16x16x128_f8f6f4 v[74:77], v[206:213], v[174:181], v[74:77], v219, v220 op_sel_hi:[0,0,0]
	v_mfma_scale_f32_16x16x128_f8f6f4 v[66:69], v[226:233], v[174:181], v[66:69], v219, v220 op_sel_hi:[0,0,0]
	v_mfma_scale_f32_16x16x128_f8f6f4 v[58:61], v[206:213], v[182:189], v[58:61], v219, v220 op_sel_hi:[0,0,0]
	v_mfma_scale_f32_16x16x128_f8f6f4 v[50:53], v[226:233], v[182:189], v[50:53], v219, v220 op_sel_hi:[0,0,0]
	v_mfma_scale_f32_16x16x128_f8f6f4 v[42:45], v[206:213], v[190:197], v[42:45], v219, v220 op_sel_hi:[0,0,0]
	v_mfma_scale_f32_16x16x128_f8f6f4 v[34:37], v[226:233], v[190:197], v[34:37], v219, v220 op_sel_hi:[0,0,0]
	v_mfma_scale_f32_16x16x128_f8f6f4 v[26:29], v[206:213], v[198:205], v[26:29], v219, v220 op_sel_hi:[0,0,0]
	v_mfma_scale_f32_16x16x128_f8f6f4 v[18:21], v[226:233], v[198:205], v[18:21], v219, v220 op_sel_hi:[0,0,0]
	s_setprio 0
	s_add_i32 s41, 0, 0x18000
	v_add_u32_e32 v14, s41, v170
	s_barrier
	ds_read_b128 v[2:5], v14
	ds_read_b128 v[6:9], v14 offset:1024
	ds_read_b128 v[10:13], v14 offset:2048
	ds_read_b128 v[14:17], v14 offset:3072
	s_add_u32 s18, s18, 0x20000
	s_addc_u32 s19, s19, 0
	s_mov_b32 m0, s25
	ds_read_b128 v[174:177], v172 offset:32768
	ds_read_b128 v[178:181], v172 offset:33792
	ds_read_b128 v[182:185], v172 offset:34816
	ds_read_b128 v[186:189], v172 offset:35840
	ds_read_b128 v[190:193], v172 offset:36864
	ds_read_b128 v[194:197], v172 offset:37888
	ds_read_b128 v[198:201], v172 offset:38912
	ds_read_b128 v[202:205], v172 offset:39936
	global_load_lds_dwordx4 v156, s[18:19]
	s_mov_b32 m0, s26
	s_nop 0
	global_load_lds_dwordx4 v152, s[18:19]
	s_waitcnt lgkmcnt(8)
	s_barrier
	s_waitcnt lgkmcnt(0)
	s_setprio 1
	s_waitcnt lgkmcnt(0)
	v_mfma_scale_f32_16x16x128_f8f6f4 v[148:151], v[2:9], v[174:181], v[148:151], v219, v220 op_sel_hi:[0,0,0]
	v_mfma_scale_f32_16x16x128_f8f6f4 v[134:137], v[10:17], v[174:181], v[134:137], v219, v220 op_sel_hi:[0,0,0]
	v_mfma_scale_f32_16x16x128_f8f6f4 v[126:129], v[2:9], v[182:189], v[126:129], v219, v220 op_sel_hi:[0,0,0]
	v_mfma_scale_f32_16x16x128_f8f6f4 v[118:121], v[10:17], v[182:189], v[118:121], v219, v220 op_sel_hi:[0,0,0]
	v_mfma_scale_f32_16x16x128_f8f6f4 v[110:113], v[2:9], v[190:197], v[110:113], v219, v220 op_sel_hi:[0,0,0]
	v_mfma_scale_f32_16x16x128_f8f6f4 v[102:105], v[10:17], v[190:197], v[102:105], v219, v220 op_sel_hi:[0,0,0]
	v_mfma_scale_f32_16x16x128_f8f6f4 v[94:97], v[2:9], v[198:205], v[94:97], v219, v220 op_sel_hi:[0,0,0]
	v_mfma_scale_f32_16x16x128_f8f6f4 v[86:89], v[10:17], v[198:205], v[86:89], v219, v220 op_sel_hi:[0,0,0]
	s_setprio 0
	s_barrier
	s_add_i32 s18, 0, 0x1c000
	s_add_i32 s19, s41, s22
	v_add_u32_e32 v173, s18, v170
	v_lshl_add_u64 v[162:163], v[162:163], 0, s[46:47]
	s_mov_b32 m0, s19
	ds_read_b128 v[206:209], v173
	ds_read_b128 v[210:213], v173 offset:1024
	ds_read_b128 v[226:229], v173 offset:2048
	ds_read_b128 v[230:233], v173 offset:3072
	global_load_lds_dwordx4 v[162:163], off
	v_lshl_add_u64 v[162:163], v[164:165], 0, s[46:47]
	s_add_i32 m0, s19, 0x2000
	s_nop 0
	global_load_lds_dwordx4 v[162:163], off
	s_barrier
	s_waitcnt lgkmcnt(0)
	s_setprio 1
	s_waitcnt lgkmcnt(0)
	v_mfma_scale_f32_16x16x128_f8f6f4 v[138:141], v[206:213], v[174:181], v[138:141], v219, v220 op_sel_hi:[0,0,0]
	v_mfma_scale_f32_16x16x128_f8f6f4 v[130:133], v[226:233], v[174:181], v[130:133], v219, v220 op_sel_hi:[0,0,0]
	v_mfma_scale_f32_16x16x128_f8f6f4 v[122:125], v[206:213], v[182:189], v[122:125], v219, v220 op_sel_hi:[0,0,0]
	v_mfma_scale_f32_16x16x128_f8f6f4 v[114:117], v[226:233], v[182:189], v[114:117], v219, v220 op_sel_hi:[0,0,0]
	v_mfma_scale_f32_16x16x128_f8f6f4 v[106:109], v[206:213], v[190:197], v[106:109], v219, v220 op_sel_hi:[0,0,0]
	v_mfma_scale_f32_16x16x128_f8f6f4 v[98:101], v[226:233], v[190:197], v[98:101], v219, v220 op_sel_hi:[0,0,0]
	v_mfma_scale_f32_16x16x128_f8f6f4 v[90:93], v[206:213], v[198:205], v[90:93], v219, v220 op_sel_hi:[0,0,0]
	v_mfma_scale_f32_16x16x128_f8f6f4 v[82:85], v[226:233], v[198:205], v[82:85], v219, v220 op_sel_hi:[0,0,0]
	s_setprio 0
	s_mov_b32 m0, s28
	v_lshl_add_u64 v[162:163], v[166:167], 0, s[46:47]
	s_barrier
	ds_read_b128 v[174:177], v172 offset:49152
	ds_read_b128 v[178:181], v172 offset:50176
	ds_read_b128 v[182:185], v172 offset:51200
	ds_read_b128 v[186:189], v172 offset:52224
	ds_read_b128 v[190:193], v172 offset:53248
	ds_read_b128 v[194:197], v172 offset:54272
	ds_read_b128 v[198:201], v172 offset:55296
	ds_read_b128 v[202:205], v172 offset:56320
	global_load_lds_dwordx4 v[162:163], off
	v_lshl_add_u64 v[162:163], v[168:169], 0, s[46:47]
	s_mov_b32 m0, s29
	s_nop 0
	global_load_lds_dwordx4 v[162:163], off
	s_barrier
	s_waitcnt lgkmcnt(0)
	s_setprio 1
	s_waitcnt lgkmcnt(0)
	v_mfma_scale_f32_16x16x128_f8f6f4 v[78:81], v[2:9], v[174:181], v[78:81], v219, v220 op_sel_hi:[0,0,0]
	v_mfma_scale_f32_16x16x128_f8f6f4 v[70:73], v[10:17], v[174:181], v[70:73], v219, v220 op_sel_hi:[0,0,0]
	v_mfma_scale_f32_16x16x128_f8f6f4 v[62:65], v[2:9], v[182:189], v[62:65], v219, v220 op_sel_hi:[0,0,0]
	v_mfma_scale_f32_16x16x128_f8f6f4 v[54:57], v[10:17], v[182:189], v[54:57], v219, v220 op_sel_hi:[0,0,0]
	v_mfma_scale_f32_16x16x128_f8f6f4 v[46:49], v[2:9], v[190:197], v[46:49], v219, v220 op_sel_hi:[0,0,0]
	v_mfma_scale_f32_16x16x128_f8f6f4 v[38:41], v[10:17], v[190:197], v[38:41], v219, v220 op_sel_hi:[0,0,0]
	v_mfma_scale_f32_16x16x128_f8f6f4 v[30:33], v[2:9], v[198:205], v[30:33], v219, v220 op_sel_hi:[0,0,0]
	v_mfma_scale_f32_16x16x128_f8f6f4 v[22:25], v[10:17], v[198:205], v[22:25], v219, v220 op_sel_hi:[0,0,0]
	s_setprio 0
	s_barrier
	s_add_u32 s16, s16, 0x20080
	s_addc_u32 s17, s17, 0
	s_add_i32 s18, s18, s22
	s_mov_b32 m0, s18
	s_nop 0
	global_load_lds_dwordx4 v154, s[16:17]
	s_add_i32 m0, s18, 0x2000
	s_nop 0
	global_load_lds_dwordx4 v142, s[16:17]
	s_waitcnt vmcnt(6)
	s_barrier
	s_setprio 1
	v_mfma_scale_f32_16x16x128_f8f6f4 v[74:77], v[206:213], v[174:181], v[74:77], v219, v220 op_sel_hi:[0,0,0]
	v_mfma_scale_f32_16x16x128_f8f6f4 v[66:69], v[226:233], v[174:181], v[66:69], v219, v220 op_sel_hi:[0,0,0]
	v_mfma_scale_f32_16x16x128_f8f6f4 v[58:61], v[206:213], v[182:189], v[58:61], v219, v220 op_sel_hi:[0,0,0]
	v_mfma_scale_f32_16x16x128_f8f6f4 v[50:53], v[226:233], v[182:189], v[50:53], v219, v220 op_sel_hi:[0,0,0]
	v_mfma_scale_f32_16x16x128_f8f6f4 v[42:45], v[206:213], v[190:197], v[42:45], v219, v220 op_sel_hi:[0,0,0]
	v_mfma_scale_f32_16x16x128_f8f6f4 v[34:37], v[226:233], v[190:197], v[34:37], v219, v220 op_sel_hi:[0,0,0]
	v_mfma_scale_f32_16x16x128_f8f6f4 v[26:29], v[206:213], v[198:205], v[26:29], v219, v220 op_sel_hi:[0,0,0]
	v_mfma_scale_f32_16x16x128_f8f6f4 v[18:21], v[226:233], v[198:205], v[18:21], v219, v220 op_sel_hi:[0,0,0]
	s_setprio 0
	s_add_u32 s14, s14, 0x100
	s_addc_u32 s15, s15, 0
	s_add_u32 s38, s38, 0x100
	s_addc_u32 s39, s39, 0
	s_cmp_ge_i32 s40, s27
	s_mov_b32 s16, s40
	s_barrier
	s_cbranch_scc0 .LBB0_1281
	v_readlane_b32 s38, v255, 8
	s_mov_b32 s37, s59
	v_mov_b32_e32 v203, v214
	v_readlane_b32 s39, v255, 9
	s_branch .LBB0_1276

.LBB0_1347:
	s_add_i32 s40, s16, 2
	s_add_u32 s17, s14, 0xfffc0080
	s_addc_u32 s18, s15, -1
	s_add_i32 s41, 0, 0x10000
	v_add_u32_e32 v14, s41, v170
	ds_read_b128 v[2:5], v14
	ds_read_b128 v[6:9], v14 offset:1024
	ds_read_b128 v[10:13], v14 offset:2048
	ds_read_b128 v[14:17], v14 offset:3072
	s_cmp_eq_u32 s30, s16
	s_cselect_b32 s16, s37, s38
	s_cselect_b32 s19, s5, s18
	s_cselect_b32 s18, s7, s17
	s_cselect_b32 s17, s36, s39
	s_add_i32 m0, s23, 0xc000
	ds_read_b128 v[174:177], v172
	ds_read_b128 v[178:181], v172 offset:1024
	ds_read_b128 v[182:185], v172 offset:2048
	ds_read_b128 v[186:189], v172 offset:3072
	ds_read_b128 v[190:193], v172 offset:4096
	ds_read_b128 v[194:197], v172 offset:5120
	ds_read_b128 v[198:201], v172 offset:6144
	ds_read_b128 v[202:205], v172 offset:7168
	global_load_lds_dwordx4 v158, s[14:15]
	s_add_i32 m0, s23, 0xe000
	s_nop 0
	global_load_lds_dwordx4 v160, s[14:15]
	s_waitcnt lgkmcnt(8)
	s_barrier
	s_waitcnt lgkmcnt(0)
	s_setprio 1
	s_waitcnt lgkmcnt(0)
	v_mfma_scale_f32_16x16x128_f8f6f4 v[138:141], v[2:9], v[174:181], v[138:141], v219, v221 op_sel_hi:[0,0,0]
	v_mfma_scale_f32_16x16x128_f8f6f4 v[148:151], v[10:17], v[174:181], v[148:151], v219, v221 op_sel_hi:[0,0,0]
	v_mfma_scale_f32_16x16x128_f8f6f4 v[126:129], v[2:9], v[182:189], v[126:129], v219, v221 op_sel_hi:[0,0,0]
	v_mfma_scale_f32_16x16x128_f8f6f4 v[122:125], v[10:17], v[182:189], v[122:125], v219, v221 op_sel_hi:[0,0,0]
	v_mfma_scale_f32_16x16x128_f8f6f4 v[110:113], v[2:9], v[190:197], v[110:113], v219, v221 op_sel_hi:[0,0,0]
	v_mfma_scale_f32_16x16x128_f8f6f4 v[106:109], v[10:17], v[190:197], v[106:109], v219, v221 op_sel_hi:[0,0,0]
	v_mfma_scale_f32_16x16x128_f8f6f4 v[94:97], v[2:9], v[198:205], v[94:97], v219, v221 op_sel_hi:[0,0,0]
	v_mfma_scale_f32_16x16x128_f8f6f4 v[90:93], v[10:17], v[198:205], v[90:93], v219, v221 op_sel_hi:[0,0,0]
	s_setprio 0
	s_barrier
	s_add_i32 s44, 0, 0x14000
	v_add_u32_e32 v162, s44, v170
	s_add_i32 s41, s41, s22
	ds_read_b128 v[206:209], v162
	ds_read_b128 v[210:213], v162 offset:1024
	ds_read_b128 v[226:229], v162 offset:2048
	ds_read_b128 v[230:233], v162 offset:3072
	v_lshl_add_u64 v[162:163], s[16:17], 0, v[154:155]
	s_mov_b32 m0, s41
	v_lshl_add_u64 v[164:165], s[16:17], 0, v[142:143]
	global_load_lds_dwordx4 v[162:163], off
	s_add_i32 m0, s41, 0x2000
	s_nop 0
	global_load_lds_dwordx4 v[164:165], off
	s_barrier
	s_waitcnt lgkmcnt(0)
	s_setprio 1
	s_waitcnt lgkmcnt(0)
	v_mfma_scale_f32_16x16x128_f8f6f4 v[134:137], v[206:213], v[174:181], v[134:137], v219, v221 op_sel_hi:[0,0,0]
	v_mfma_scale_f32_16x16x128_f8f6f4 v[130:133], v[226:233], v[174:181], v[130:133], v219, v221 op_sel_hi:[0,0,0]
	v_mfma_scale_f32_16x16x128_f8f6f4 v[118:121], v[206:213], v[182:189], v[118:121], v219, v221 op_sel_hi:[0,0,0]
	v_mfma_scale_f32_16x16x128_f8f6f4 v[114:117], v[226:233], v[182:189], v[114:117], v219, v221 op_sel_hi:[0,0,0]
	v_mfma_scale_f32_16x16x128_f8f6f4 v[102:105], v[206:213], v[190:197], v[102:105], v219, v221 op_sel_hi:[0,0,0]
	v_mfma_scale_f32_16x16x128_f8f6f4 v[98:101], v[226:233], v[190:197], v[98:101], v219, v221 op_sel_hi:[0,0,0]
	v_mfma_scale_f32_16x16x128_f8f6f4 v[86:89], v[206:213], v[198:205], v[86:89], v219, v221 op_sel_hi:[0,0,0]
	v_mfma_scale_f32_16x16x128_f8f6f4 v[82:85], v[226:233], v[198:205], v[82:85], v219, v221 op_sel_hi:[0,0,0]
	s_setprio 0
	s_mov_b32 m0, s23
	v_lshl_add_u64 v[166:167], s[18:19], 0, v[156:157]
	s_barrier
	ds_read_b128 v[174:177], v172 offset:16384
	ds_read_b128 v[178:181], v172 offset:17408
	ds_read_b128 v[182:185], v172 offset:18432
	ds_read_b128 v[186:189], v172 offset:19456
	ds_read_b128 v[190:193], v172 offset:20480
	ds_read_b128 v[194:197], v172 offset:21504
	ds_read_b128 v[198:201], v172 offset:22528
	ds_read_b128 v[202:205], v172 offset:23552
	global_load_lds_dwordx4 v[166:167], off
	v_lshl_add_u64 v[168:169], s[18:19], 0, v[152:153]
	s_mov_b32 m0, s24
	s_nop 0
	global_load_lds_dwordx4 v[168:169], off
	s_barrier
	s_waitcnt lgkmcnt(0)
	s_setprio 1
	s_waitcnt lgkmcnt(0)
	v_mfma_scale_f32_16x16x128_f8f6f4 v[78:81], v[2:9], v[174:181], v[78:81], v219, v221 op_sel_hi:[0,0,0]
	v_mfma_scale_f32_16x16x128_f8f6f4 v[74:77], v[10:17], v[174:181], v[74:77], v219, v221 op_sel_hi:[0,0,0]
	v_mfma_scale_f32_16x16x128_f8f6f4 v[62:65], v[2:9], v[182:189], v[62:65], v219, v221 op_sel_hi:[0,0,0]
	v_mfma_scale_f32_16x16x128_f8f6f4 v[58:61], v[10:17], v[182:189], v[58:61], v219, v221 op_sel_hi:[0,0,0]
	v_mfma_scale_f32_16x16x128_f8f6f4 v[46:49], v[2:9], v[190:197], v[46:49], v219, v221 op_sel_hi:[0,0,0]
	v_mfma_scale_f32_16x16x128_f8f6f4 v[42:45], v[10:17], v[190:197], v[42:45], v219, v221 op_sel_hi:[0,0,0]
	v_mfma_scale_f32_16x16x128_f8f6f4 v[30:33], v[2:9], v[198:205], v[30:33], v219, v221 op_sel_hi:[0,0,0]
	v_mfma_scale_f32_16x16x128_f8f6f4 v[26:29], v[10:17], v[198:205], v[26:29], v219, v221 op_sel_hi:[0,0,0]
	s_setprio 0
	s_barrier
	s_add_u32 s42, s16, 0x40000
	s_addc_u32 s43, s17, 0
	s_add_i32 s41, s44, s22
	s_mov_b32 m0, s41
	s_nop 0
	global_load_lds_dwordx4 v154, s[42:43]
	s_add_i32 m0, s41, 0x2000
	s_nop 0
	global_load_lds_dwordx4 v142, s[42:43]
	s_waitcnt vmcnt(6)
	s_barrier
	s_setprio 1
	v_mfma_scale_f32_16x16x128_f8f6f4 v[70:73], v[206:213], v[174:181], v[70:73], v219, v221 op_sel_hi:[0,0,0]
	v_mfma_scale_f32_16x16x128_f8f6f4 v[66:69], v[226:233], v[174:181], v[66:69], v219, v221 op_sel_hi:[0,0,0]
	v_mfma_scale_f32_16x16x128_f8f6f4 v[54:57], v[206:213], v[182:189], v[54:57], v219, v221 op_sel_hi:[0,0,0]
	v_mfma_scale_f32_16x16x128_f8f6f4 v[50:53], v[226:233], v[182:189], v[50:53], v219, v221 op_sel_hi:[0,0,0]
	v_mfma_scale_f32_16x16x128_f8f6f4 v[38:41], v[206:213], v[190:197], v[38:41], v219, v221 op_sel_hi:[0,0,0]
	v_mfma_scale_f32_16x16x128_f8f6f4 v[34:37], v[226:233], v[190:197], v[34:37], v219, v221 op_sel_hi:[0,0,0]
	v_mfma_scale_f32_16x16x128_f8f6f4 v[22:25], v[206:213], v[198:205], v[22:25], v219, v221 op_sel_hi:[0,0,0]
	v_mfma_scale_f32_16x16x128_f8f6f4 v[18:21], v[226:233], v[198:205], v[18:21], v219, v221 op_sel_hi:[0,0,0]
	s_setprio 0
	s_add_i32 s41, 0, 0x18000
	v_add_u32_e32 v14, s41, v170
	s_barrier
	ds_read_b128 v[2:5], v14
	ds_read_b128 v[6:9], v14 offset:1024
	ds_read_b128 v[10:13], v14 offset:2048
	ds_read_b128 v[14:17], v14 offset:3072
	s_add_u32 s18, s18, 0x40000
	s_addc_u32 s19, s19, 0
	s_mov_b32 m0, s25
	ds_read_b128 v[174:177], v172 offset:32768
	ds_read_b128 v[178:181], v172 offset:33792
	ds_read_b128 v[182:185], v172 offset:34816
	ds_read_b128 v[186:189], v172 offset:35840
	ds_read_b128 v[190:193], v172 offset:36864
	ds_read_b128 v[194:197], v172 offset:37888
	ds_read_b128 v[198:201], v172 offset:38912
	ds_read_b128 v[202:205], v172 offset:39936
	global_load_lds_dwordx4 v156, s[18:19]
	s_mov_b32 m0, s26
	s_nop 0
	global_load_lds_dwordx4 v152, s[18:19]
	s_waitcnt lgkmcnt(8)
	s_barrier
	s_waitcnt lgkmcnt(0)
	s_setprio 1
	s_waitcnt lgkmcnt(0)
	v_mfma_scale_f32_16x16x128_f8f6f4 v[138:141], v[2:9], v[174:181], v[138:141], v219, v221 op_sel_hi:[0,0,0]
	v_mfma_scale_f32_16x16x128_f8f6f4 v[148:151], v[10:17], v[174:181], v[148:151], v219, v221 op_sel_hi:[0,0,0]
	v_mfma_scale_f32_16x16x128_f8f6f4 v[126:129], v[2:9], v[182:189], v[126:129], v219, v221 op_sel_hi:[0,0,0]
	v_mfma_scale_f32_16x16x128_f8f6f4 v[122:125], v[10:17], v[182:189], v[122:125], v219, v221 op_sel_hi:[0,0,0]
	v_mfma_scale_f32_16x16x128_f8f6f4 v[110:113], v[2:9], v[190:197], v[110:113], v219, v221 op_sel_hi:[0,0,0]
	v_mfma_scale_f32_16x16x128_f8f6f4 v[106:109], v[10:17], v[190:197], v[106:109], v219, v221 op_sel_hi:[0,0,0]
	v_mfma_scale_f32_16x16x128_f8f6f4 v[94:97], v[2:9], v[198:205], v[94:97], v219, v221 op_sel_hi:[0,0,0]
	v_mfma_scale_f32_16x16x128_f8f6f4 v[90:93], v[10:17], v[198:205], v[90:93], v219, v221 op_sel_hi:[0,0,0]
	s_setprio 0
	s_barrier
	s_add_i32 s18, 0, 0x1c000
	s_add_i32 s19, s41, s22
	v_add_u32_e32 v173, s18, v170
	v_lshl_add_u64 v[162:163], v[162:163], 0, s[46:47]
	s_mov_b32 m0, s19
	ds_read_b128 v[206:209], v173
	ds_read_b128 v[210:213], v173 offset:1024
	ds_read_b128 v[226:229], v173 offset:2048
	ds_read_b128 v[230:233], v173 offset:3072
	global_load_lds_dwordx4 v[162:163], off
	v_lshl_add_u64 v[162:163], v[164:165], 0, s[46:47]
	s_add_i32 m0, s19, 0x2000
	s_nop 0
	global_load_lds_dwordx4 v[162:163], off
	s_barrier
	s_waitcnt lgkmcnt(0)
	s_setprio 1
	s_waitcnt lgkmcnt(0)
	v_mfma_scale_f32_16x16x128_f8f6f4 v[134:137], v[206:213], v[174:181], v[134:137], v219, v221 op_sel_hi:[0,0,0]
	v_mfma_scale_f32_16x16x128_f8f6f4 v[130:133], v[226:233], v[174:181], v[130:133], v219, v221 op_sel_hi:[0,0,0]
	v_mfma_scale_f32_16x16x128_f8f6f4 v[118:121], v[206:213], v[182:189], v[118:121], v219, v221 op_sel_hi:[0,0,0]
	v_mfma_scale_f32_16x16x128_f8f6f4 v[114:117], v[226:233], v[182:189], v[114:117], v219, v221 op_sel_hi:[0,0,0]
	v_mfma_scale_f32_16x16x128_f8f6f4 v[102:105], v[206:213], v[190:197], v[102:105], v219, v221 op_sel_hi:[0,0,0]
	v_mfma_scale_f32_16x16x128_f8f6f4 v[98:101], v[226:233], v[190:197], v[98:101], v219, v221 op_sel_hi:[0,0,0]
	v_mfma_scale_f32_16x16x128_f8f6f4 v[86:89], v[206:213], v[198:205], v[86:89], v219, v221 op_sel_hi:[0,0,0]
	v_mfma_scale_f32_16x16x128_f8f6f4 v[82:85], v[226:233], v[198:205], v[82:85], v219, v221 op_sel_hi:[0,0,0]
	s_setprio 0
	s_mov_b32 m0, s28
	v_lshl_add_u64 v[162:163], v[166:167], 0, s[46:47]
	s_barrier
	ds_read_b128 v[174:177], v172 offset:49152
	ds_read_b128 v[178:181], v172 offset:50176
	ds_read_b128 v[182:185], v172 offset:51200
	ds_read_b128 v[186:189], v172 offset:52224
	ds_read_b128 v[190:193], v172 offset:53248
	ds_read_b128 v[194:197], v172 offset:54272
	ds_read_b128 v[198:201], v172 offset:55296
	ds_read_b128 v[202:205], v172 offset:56320
	global_load_lds_dwordx4 v[162:163], off
	v_lshl_add_u64 v[162:163], v[168:169], 0, s[46:47]
	s_mov_b32 m0, s29
	s_nop 0
	global_load_lds_dwordx4 v[162:163], off
	s_barrier
	s_waitcnt lgkmcnt(0)
	s_setprio 1
	s_waitcnt lgkmcnt(0)
	v_mfma_scale_f32_16x16x128_f8f6f4 v[78:81], v[2:9], v[174:181], v[78:81], v219, v221 op_sel_hi:[0,0,0]
	v_mfma_scale_f32_16x16x128_f8f6f4 v[74:77], v[10:17], v[174:181], v[74:77], v219, v221 op_sel_hi:[0,0,0]
	v_mfma_scale_f32_16x16x128_f8f6f4 v[62:65], v[2:9], v[182:189], v[62:65], v219, v221 op_sel_hi:[0,0,0]
	v_mfma_scale_f32_16x16x128_f8f6f4 v[58:61], v[10:17], v[182:189], v[58:61], v219, v221 op_sel_hi:[0,0,0]
	v_mfma_scale_f32_16x16x128_f8f6f4 v[46:49], v[2:9], v[190:197], v[46:49], v219, v221 op_sel_hi:[0,0,0]
	v_mfma_scale_f32_16x16x128_f8f6f4 v[42:45], v[10:17], v[190:197], v[42:45], v219, v221 op_sel_hi:[0,0,0]
	v_mfma_scale_f32_16x16x128_f8f6f4 v[30:33], v[2:9], v[198:205], v[30:33], v219, v221 op_sel_hi:[0,0,0]
	v_mfma_scale_f32_16x16x128_f8f6f4 v[26:29], v[10:17], v[198:205], v[26:29], v219, v221 op_sel_hi:[0,0,0]
	s_setprio 0
	s_barrier
	s_add_u32 s16, s16, 0x40080
	s_addc_u32 s17, s17, 0
	s_add_i32 s18, s18, s22
	s_mov_b32 m0, s18
	s_nop 0
	global_load_lds_dwordx4 v154, s[16:17]
	s_add_i32 m0, s18, 0x2000
	s_nop 0
	global_load_lds_dwordx4 v142, s[16:17]
	s_waitcnt vmcnt(6)
	s_barrier
	s_setprio 1
	v_mfma_scale_f32_16x16x128_f8f6f4 v[70:73], v[206:213], v[174:181], v[70:73], v219, v221 op_sel_hi:[0,0,0]
	v_mfma_scale_f32_16x16x128_f8f6f4 v[66:69], v[226:233], v[174:181], v[66:69], v219, v221 op_sel_hi:[0,0,0]
	v_mfma_scale_f32_16x16x128_f8f6f4 v[54:57], v[206:213], v[182:189], v[54:57], v219, v221 op_sel_hi:[0,0,0]
	v_mfma_scale_f32_16x16x128_f8f6f4 v[50:53], v[226:233], v[182:189], v[50:53], v219, v221 op_sel_hi:[0,0,0]
	v_mfma_scale_f32_16x16x128_f8f6f4 v[38:41], v[206:213], v[190:197], v[38:41], v219, v221 op_sel_hi:[0,0,0]
	v_mfma_scale_f32_16x16x128_f8f6f4 v[34:37], v[226:233], v[190:197], v[34:37], v219, v221 op_sel_hi:[0,0,0]
	v_mfma_scale_f32_16x16x128_f8f6f4 v[22:25], v[206:213], v[198:205], v[22:25], v219, v221 op_sel_hi:[0,0,0]
	v_mfma_scale_f32_16x16x128_f8f6f4 v[18:21], v[226:233], v[198:205], v[18:21], v219, v221 op_sel_hi:[0,0,0]
	s_setprio 0
	s_add_u32 s14, s14, 0x100
	s_addc_u32 s15, s15, 0
	s_add_u32 s38, s38, 0x100
	s_addc_u32 s39, s39, 0
	s_cmp_ge_i32 s40, s27
	s_mov_b32 s16, s40
	s_barrier
	s_cbranch_scc0 .LBB0_1347
	v_readlane_b32 s38, v255, 8
	s_mov_b32 s37, s59
	v_mov_b32_e32 v203, v214
	v_readlane_b32 s39, v255, 9
	s_branch .LBB0_1342
